# attention loop v2: -mrun folded into QK accumulator init, merged lgkm waits, ILP-ordered softmax, rescale trigger from tile row-sum, even VALU spread
# speedup vs baseline: 1.0581x; 1.0242x over previous
; DEV float max3f(float a, float b, float c) { return fmaxf(fmaxf(a, b), c); }
; #define LOADK(t) do { const long kb_ = KBASE(t); kreg0 = *(const u32x4*)(K + (kb_ + lane) * 1536 + h * 96 + wid * 8); \
;         if (k2) kreg1 = *(const u32x4*)(K + (kb_ + lane) * 1536 + h * 96 + (8 + wid) * 8); } while (0)
; #define LOADV(t) do { const long kb_ = KBASE(t); vreg = *(const u32x4*)(V + (kb_ + 16 * (wid & 3) + (lane >> 2)) * 1024 + h * 64 + (wid >> 2) * 32 + (lane & 3) * 8); } while (0)
; #define STOREK(s) do { LAS unsigned char* st_ = sh + (s) * STG; *(LAS u32x4*)(st_ + wid * 1024 + lane * 16) = kreg0; if (k2) *(LAS u32x4*)(st_ + (8 + wid) * 1024 + lane * 16) = kreg1; } while (0)
; #define STOREV(s) do { LAS unsigned char* st_ = sh + (s) * STG; *(LAS u32x4*)(st_ + KST + wid * 1024 + lane * 16) = vreg; } while (0)
; DEV void attn_unit(int b, int h, int qb, const bf16_t* Q, const bf16_t* K, const bf16_t* V, bf16_t* O, LAS unsigned char* sh, const int tid, const float* qgain) {
;     ...
;     LOADK(0); LOADV(0); STOREK(0); STOREV(0); LOADK(1); STOREK(1); __syncthreads();
;     f32x16 pA0, pA1, pB0 = f32x16{}, pB1 = f32x16{};
;     QKT(pA0, pA1, 0);
;     { float m0 = pA0[0];
; #pragma unroll
;         for (int r = 0; r < 16; ++r) m0 = max3f(m0, pA0[r], pA1[r]);
;         mrun = fmaxf(m0, __shfl_xor(m0, 32)); }
.Lat_k2_3:
	s_add_u32 s12, s12, 0x30000
	s_addc_u32 s13, s13, 0
	v_mov_b32_e32 v0, 0
	v_mov_b32_e32 v1, 0
	v_mov_b32_e32 v2, 0
	v_mov_b32_e32 v3, 0
	v_mov_b32_e32 v4, 0
	v_mov_b32_e32 v5, 0
	v_mov_b32_e32 v6, 0
	v_mov_b32_e32 v7, 0
	v_mov_b32_e32 v8, 0
	v_mov_b32_e32 v9, 0
	v_mov_b32_e32 v10, 0
	v_mov_b32_e32 v11, 0
	v_mov_b32_e32 v12, 0
	v_mov_b32_e32 v13, 0
	v_mov_b32_e32 v14, 0
	v_mov_b32_e32 v15, 0
	v_mov_b32_e32 v16, 0
	v_mov_b32_e32 v17, 0
	v_mov_b32_e32 v18, 0
	v_mov_b32_e32 v19, 0
	v_mov_b32_e32 v20, 0
	v_mov_b32_e32 v21, 0
	v_mov_b32_e32 v22, 0
	v_mov_b32_e32 v23, 0
	v_mov_b32_e32 v24, 0
	v_mov_b32_e32 v25, 0
	v_mov_b32_e32 v26, 0
	v_mov_b32_e32 v27, 0
	v_mov_b32_e32 v28, 0
	v_mov_b32_e32 v29, 0
	v_mov_b32_e32 v30, 0
	v_mov_b32_e32 v31, 0
	v_mov_b32_e32 v147, 0
	s_waitcnt vmcnt(0)
	s_barrier
	ds_read_b128 v[196:199], v194 offset:0
	ds_read_b128 v[200:203], v194 offset:512
	ds_read_b128 v[204:207], v194 offset:2048
	ds_read_b128 v[208:211], v194 offset:2560
	ds_read_b128 v[212:215], v194 offset:4096
	ds_read_b128 v[216:219], v194 offset:4608
	s_waitcnt lgkmcnt(4)
	v_mfma_f32_32x32x16_bf16 v[48:63], v[196:199], v[110:113], 0
	ds_read_b128 v[196:199], v194 offset:6144
	v_mfma_f32_32x32x16_bf16 v[32:47], v[200:203], v[110:113], 0
	ds_read_b128 v[200:203], v194 offset:6656
	s_waitcnt lgkmcnt(4)
	v_mfma_f32_32x32x16_bf16 v[48:63], v[204:207], v[106:109], v[48:63]
	ds_read_b128 v[204:207], v194 offset:8192
	v_mfma_f32_32x32x16_bf16 v[32:47], v[208:211], v[106:109], v[32:47]
	ds_read_b128 v[208:211], v194 offset:8704
	s_waitcnt lgkmcnt(4)
	v_mfma_f32_32x32x16_bf16 v[48:63], v[212:215], v[114:117], v[48:63]
	ds_read_b128 v[212:215], v194 offset:10240
	v_mfma_f32_32x32x16_bf16 v[32:47], v[216:219], v[114:117], v[32:47]
	ds_read_b128 v[216:219], v194 offset:10752
	s_waitcnt lgkmcnt(4)
	v_mfma_f32_32x32x16_bf16 v[48:63], v[196:199], v[118:121], v[48:63]
	v_mfma_f32_32x32x16_bf16 v[32:47], v[200:203], v[118:121], v[32:47]
	s_waitcnt lgkmcnt(2)
	v_mfma_f32_32x32x16_bf16 v[48:63], v[204:207], v[102:105], v[48:63]
	v_mfma_f32_32x32x16_bf16 v[32:47], v[208:211], v[102:105], v[32:47]
	s_waitcnt lgkmcnt(0)
	v_mfma_f32_32x32x16_bf16 v[48:63], v[212:215], v[98:101], v[48:63]
	v_mfma_f32_32x32x16_bf16 v[32:47], v[216:219], v[98:101], v[32:47]
	s_nop 15
	s_nop 3
	v_max_f32_e32 v149, v48, v32
	v_max3_f32 v149, v149, v49, v33
	v_max3_f32 v149, v149, v50, v34
	v_max3_f32 v149, v149, v51, v35
	v_max3_f32 v149, v149, v52, v36
	v_max3_f32 v149, v149, v53, v37
	v_max3_f32 v149, v149, v54, v38
	v_max3_f32 v149, v149, v55, v39
	v_max3_f32 v149, v149, v56, v40
	v_max3_f32 v149, v149, v57, v41
	v_max3_f32 v149, v149, v58, v42
	v_max3_f32 v149, v149, v59, v43
	v_max3_f32 v149, v149, v60, v44
	v_max3_f32 v149, v149, v61, v45
	v_max3_f32 v149, v149, v62, v46
	v_max3_f32 v149, v149, v63, v47
	v_mov_b32_e32 v175, v149
	v_mov_b32_e32 v178, v149
	s_nop 1
	v_permlane32_swap_b32_e32 v175, v178
	v_max_f32_e32 v175, v175, v178
	v_xor_b32_e32 v224, 0x80000000, v175
	v_mov_b32_e32 v225, v224
	v_mov_b32_e32 v226, v224
	v_mov_b32_e32 v227, v224
	v_mov_b32_e32 v228, v224
	v_mov_b32_e32 v229, v224
	v_mov_b32_e32 v230, v224
	v_mov_b32_e32 v231, v224
	v_mov_b32_e32 v232, v224
	v_mov_b32_e32 v233, v224
	v_mov_b32_e32 v234, v224
	v_mov_b32_e32 v235, v224
	v_mov_b32_e32 v236, v224
	v_mov_b32_e32 v237, v224
	v_mov_b32_e32 v238, v224
	v_mov_b32_e32 v239, v224
	v_sub_f32_e32 v48, v48, v175
	v_sub_f32_e32 v49, v49, v175
	v_sub_f32_e32 v50, v50, v175
	v_sub_f32_e32 v51, v51, v175
	v_sub_f32_e32 v52, v52, v175
	v_sub_f32_e32 v53, v53, v175
	v_sub_f32_e32 v54, v54, v175
	v_sub_f32_e32 v55, v55, v175
	v_sub_f32_e32 v56, v56, v175
	v_sub_f32_e32 v57, v57, v175
	v_sub_f32_e32 v58, v58, v175
	v_sub_f32_e32 v59, v59, v175
	v_sub_f32_e32 v60, v60, v175
	v_sub_f32_e32 v61, v61, v175
	v_sub_f32_e32 v62, v62, v175
	v_sub_f32_e32 v63, v63, v175
	v_sub_f32_e32 v32, v32, v175
	v_sub_f32_e32 v33, v33, v175
	v_sub_f32_e32 v34, v34, v175
	v_sub_f32_e32 v35, v35, v175
	v_sub_f32_e32 v36, v36, v175
	v_sub_f32_e32 v37, v37, v175
	v_sub_f32_e32 v38, v38, v175
	v_sub_f32_e32 v39, v39, v175
	v_sub_f32_e32 v40, v40, v175
	v_sub_f32_e32 v41, v41, v175
	v_sub_f32_e32 v42, v42, v175
	v_sub_f32_e32 v43, v43, v175
	v_sub_f32_e32 v44, v44, v175
	v_sub_f32_e32 v45, v45, v175
	v_sub_f32_e32 v46, v46, v175
	v_sub_f32_e32 v47, v47, v175
	s_mov_b32 s24, 15
.Lat_loop_4:
	ds_read_b128 v[196:199], v194 offset:20480
	ds_read_b128 v[200:203], v194 offset:20992
	ds_read_b128 v[204:207], v194 offset:22528
	ds_read_b128 v[208:211], v194 offset:23040
	ds_read_b128 v[212:215], v194 offset:24576
	ds_read_b128 v[216:219], v194 offset:25088
	ds_read_b64_tr_b16 v[220:221], v139 offset:0
	ds_read_b64_tr_b16 v[222:223], v139 offset:512
	ds_read_b64_tr_b16 v[244:245], v139 offset:4096
	ds_read_b64_tr_b16 v[246:247], v139 offset:4608
	s_add_i32 m0, s22, 0x15000
	s_cmp_eq_u32 s23, 0
	global_load_lds_dwordx4 v128, s[12:13]
	s_cbranch_scc1 .Lat_k2_5
	s_add_i32 m0, s22, 0x17000
	s_nop 0
	global_load_lds_dwordx4 v129, s[12:13]
.Lat_k2_5:
	s_add_u32 s12, s12, 0x30000
	s_addc_u32 s13, s13, 0
	s_add_i32 m0, s22, 0x13000
	s_nop 0
	global_load_lds_dwordx4 v145, s[14:15]
	s_add_u32 s14, s14, 0x20000
	s_addc_u32 s15, s15, 0
	v_exp_f32_e32 v48, v48
	v_exp_f32_e32 v49, v49
	v_exp_f32_e32 v50, v50
	v_exp_f32_e32 v51, v51
	v_mov_b32_e32 v176, v48
	v_mov_b32_e32 v177, v49
	v_cvt_pk_bf16_f32 v48, v48, v49
	v_add_f32_e32 v176, v50, v176
	v_add_f32_e32 v177, v51, v177
	v_cvt_pk_bf16_f32 v49, v50, v51
	v_exp_f32_e32 v52, v52
	v_exp_f32_e32 v53, v53
	s_waitcnt lgkmcnt(8)
	v_mfma_f32_32x32x16_bf16 v[80:95], v[196:199], v[110:113], v[224:239]
	ds_read_b128 v[196:199], v194 offset:26624
	ds_read_b64_tr_b16 v[240:241], v139 offset:1024
	ds_read_b64_tr_b16 v[242:243], v139 offset:1536
	v_exp_f32_e32 v54, v54
	v_exp_f32_e32 v55, v55
	v_add_f32_e32 v176, v52, v176
	v_add_f32_e32 v177, v53, v177
	v_mfma_f32_32x32x16_bf16 v[64:79], v[200:203], v[110:113], v[224:239]
	ds_read_b128 v[200:203], v194 offset:27136
	ds_read_b64_tr_b16 v[122:123], v139 offset:5120
	ds_read_b64_tr_b16 v[124:125], v139 offset:5632
	v_cvt_pk_bf16_f32 v50, v52, v53
	v_add_f32_e32 v176, v54, v176
	v_add_f32_e32 v177, v55, v177
	v_cvt_pk_bf16_f32 v51, v54, v55
	s_waitcnt lgkmcnt(12)
	v_mfma_f32_32x32x16_bf16 v[80:95], v[204:207], v[106:109], v[80:95]
	ds_read_b128 v[204:207], v194 offset:28672
	v_exp_f32_e32 v56, v56
	v_exp_f32_e32 v57, v57
	v_exp_f32_e32 v58, v58
	v_exp_f32_e32 v59, v59
	v_mfma_f32_32x32x16_bf16 v[64:79], v[208:211], v[106:109], v[64:79]
	ds_read_b128 v[208:211], v194 offset:29184
	v_add_f32_e32 v176, v56, v176
	v_add_f32_e32 v177, v57, v177
	v_cvt_pk_bf16_f32 v52, v56, v57
	v_add_f32_e32 v176, v58, v176
	s_waitcnt lgkmcnt(12)
	v_mfma_f32_32x32x16_bf16 v[80:95], v[212:215], v[114:117], v[80:95]
	ds_read_b128 v[212:215], v194 offset:30720
	v_add_f32_e32 v177, v59, v177
	v_cvt_pk_bf16_f32 v53, v58, v59
	v_exp_f32_e32 v60, v60
	v_exp_f32_e32 v61, v61
	s_waitcnt lgkmcnt(9)
	v_mfma_f32_32x32x16_bf16 v[0:15], v[48:51], v[220:223], v[0:15]
	ds_read_b64_tr_b16 v[220:221], v139 offset:2048
	ds_read_b64_tr_b16 v[222:223], v139 offset:2560
	v_exp_f32_e32 v62, v62
	v_exp_f32_e32 v63, v63
	v_add_f32_e32 v176, v60, v176
	v_add_f32_e32 v177, v61, v177
	v_mfma_f32_32x32x16_bf16 v[16:31], v[48:51], v[244:247], v[16:31]
	ds_read_b64_tr_b16 v[244:245], v139 offset:6144
	ds_read_b64_tr_b16 v[246:247], v139 offset:6656
	v_cvt_pk_bf16_f32 v54, v60, v61
	v_add_f32_e32 v176, v62, v176
	v_add_f32_e32 v177, v63, v177
	v_cvt_pk_bf16_f32 v55, v62, v63
	v_mfma_f32_32x32x16_bf16 v[64:79], v[216:219], v[114:117], v[64:79]
	ds_read_b128 v[216:219], v194 offset:31232
	v_exp_f32_e32 v32, v32
	v_exp_f32_e32 v33, v33
	v_exp_f32_e32 v34, v34
	v_exp_f32_e32 v35, v35
	s_waitcnt lgkmcnt(10)
	v_mfma_f32_32x32x16_bf16 v[80:95], v[196:199], v[118:121], v[80:95]
	v_add_f32_e32 v176, v32, v176
	v_add_f32_e32 v177, v33, v177
	v_cvt_pk_bf16_f32 v32, v32, v33
	v_add_f32_e32 v176, v34, v176
	v_mfma_f32_32x32x16_bf16 v[64:79], v[200:203], v[118:121], v[64:79]
	v_add_f32_e32 v177, v35, v177
	v_cvt_pk_bf16_f32 v33, v34, v35
	v_exp_f32_e32 v36, v36
	v_exp_f32_e32 v37, v37
	s_waitcnt lgkmcnt(8)
	v_mfma_f32_32x32x16_bf16 v[0:15], v[52:55], v[240:243], v[0:15]
	ds_read_b64_tr_b16 v[240:241], v139 offset:3072
	ds_read_b64_tr_b16 v[242:243], v139 offset:3584
	v_exp_f32_e32 v38, v38
	v_exp_f32_e32 v39, v39
	v_add_f32_e32 v176, v36, v176
	v_add_f32_e32 v177, v37, v177
	v_mfma_f32_32x32x16_bf16 v[16:31], v[52:55], v[122:125], v[16:31]
	ds_read_b64_tr_b16 v[122:123], v139 offset:7168
	ds_read_b64_tr_b16 v[124:125], v139 offset:7680
	v_cvt_pk_bf16_f32 v34, v36, v37
	v_add_f32_e32 v176, v38, v176
	v_add_f32_e32 v177, v39, v177
	v_cvt_pk_bf16_f32 v35, v38, v39
	s_waitcnt lgkmcnt(10)
	v_mfma_f32_32x32x16_bf16 v[80:95], v[204:207], v[102:105], v[80:95]
	v_exp_f32_e32 v40, v40
	v_exp_f32_e32 v41, v41
	v_exp_f32_e32 v42, v42
	v_exp_f32_e32 v43, v43
	v_mfma_f32_32x32x16_bf16 v[64:79], v[208:211], v[102:105], v[64:79]
	v_add_f32_e32 v176, v40, v176
	v_add_f32_e32 v177, v41, v177
	v_cvt_pk_bf16_f32 v36, v40, v41
	v_add_f32_e32 v176, v42, v176
	s_waitcnt lgkmcnt(5)
	v_mfma_f32_32x32x16_bf16 v[0:15], v[32:35], v[220:223], v[0:15]
	v_add_f32_e32 v177, v43, v177
	v_cvt_pk_bf16_f32 v37, v42, v43
	v_exp_f32_e32 v44, v44
	v_exp_f32_e32 v45, v45
	v_mfma_f32_32x32x16_bf16 v[16:31], v[32:35], v[244:247], v[16:31]
	v_exp_f32_e32 v46, v46
	v_exp_f32_e32 v47, v47
	v_add_f32_e32 v176, v44, v176
	v_add_f32_e32 v177, v45, v177
	s_waitcnt lgkmcnt(4)
	v_mfma_f32_32x32x16_bf16 v[80:95], v[212:215], v[98:101], v[80:95]
	v_cvt_pk_bf16_f32 v38, v44, v45
	v_add_f32_e32 v176, v46, v176
	v_add_f32_e32 v177, v47, v177
	v_cvt_pk_bf16_f32 v39, v46, v47
	v_mfma_f32_32x32x16_bf16 v[64:79], v[216:219], v[98:101], v[64:79]
	v_add_f32_e32 v175, v176, v177
	v_mov_b32_e32 v178, v175
	v_add_f32_e32 v147, v147, v175
	s_nop 0
	s_waitcnt lgkmcnt(0)
	v_mfma_f32_32x32x16_bf16 v[0:15], v[36:39], v[240:243], v[0:15]
	v_permlane32_swap_b32_e32 v175, v178
	v_add_f32_e32 v175, v175, v178
	v_cmp_lt_f32_e32 vcc, 0x43800000, v175
	v_mfma_f32_32x32x16_bf16 v[16:31], v[36:39], v[122:125], v[16:31]
	s_cbranch_vccz .Lat_nr_6
	v_log_f32_e32 v175, v175
	s_nop 0
	v_max_f32_e32 v175, 0, v175
	v_exp_f32_e64 v178, -v175
	s_and_saveexec_b64 s[4:5], s[2:3]
	ds_write_b32 v143, v178 offset:40960
	s_or_b64 exec, exec, s[4:5]
	s_waitcnt lgkmcnt(0)
	v_add_u32_e32 v179, s33, v191
	v_sub_f32_e32 v224, v224, v175
	v_mul_f32_e32 v147, v147, v178
	ds_read_b128 v[196:199], v179 offset:40960
	ds_read_b128 v[200:203], v179 offset:40992
	ds_read_b128 v[204:207], v179 offset:41024
	ds_read_b128 v[208:211], v179 offset:41056
	s_waitcnt lgkmcnt(0)
	s_nop 15
	v_pk_mul_f32 v[0:1], v[0:1], v[196:197]
	v_pk_mul_f32 v[2:3], v[2:3], v[198:199]
	v_pk_mul_f32 v[4:5], v[4:5], v[200:201]
	v_pk_mul_f32 v[6:7], v[6:7], v[202:203]
	v_pk_mul_f32 v[8:9], v[8:9], v[204:205]
	v_pk_mul_f32 v[10:11], v[10:11], v[206:207]
	v_pk_mul_f32 v[12:13], v[12:13], v[208:209]
	v_pk_mul_f32 v[14:15], v[14:15], v[210:211]
	v_pk_mul_f32 v[16:17], v[16:17], v[196:197]
	v_pk_mul_f32 v[18:19], v[18:19], v[198:199]
	v_pk_mul_f32 v[20:21], v[20:21], v[200:201]
	v_pk_mul_f32 v[22:23], v[22:23], v[202:203]
	v_pk_mul_f32 v[24:25], v[24:25], v[204:205]
	v_pk_mul_f32 v[26:27], v[26:27], v[206:207]
	v_pk_mul_f32 v[28:29], v[28:29], v[208:209]
	v_pk_mul_f32 v[30:31], v[30:31], v[210:211]
	v_mov_b32_e32 v225, v224
	v_mov_b32_e32 v226, v224
	v_mov_b32_e32 v227, v224
	v_mov_b32_e32 v228, v224
	v_mov_b32_e32 v229, v224
	v_mov_b32_e32 v230, v224
	v_mov_b32_e32 v231, v224
	v_mov_b32_e32 v232, v224
	v_mov_b32_e32 v233, v224
	v_mov_b32_e32 v234, v224
	v_mov_b32_e32 v235, v224
	v_mov_b32_e32 v236, v224
	v_mov_b32_e32 v237, v224
	v_mov_b32_e32 v238, v224
	v_mov_b32_e32 v239, v224
	v_sub_f32_e32 v80, v80, v175
	v_sub_f32_e32 v81, v81, v175
	v_sub_f32_e32 v82, v82, v175
	v_sub_f32_e32 v83, v83, v175
	v_sub_f32_e32 v84, v84, v175
	v_sub_f32_e32 v85, v85, v175
	v_sub_f32_e32 v86, v86, v175
	v_sub_f32_e32 v87, v87, v175
	v_sub_f32_e32 v88, v88, v175
	v_sub_f32_e32 v89, v89, v175
	v_sub_f32_e32 v90, v90, v175
	v_sub_f32_e32 v91, v91, v175
	v_sub_f32_e32 v92, v92, v175
	v_sub_f32_e32 v93, v93, v175
	v_sub_f32_e32 v94, v94, v175
	v_sub_f32_e32 v95, v95, v175
	v_sub_f32_e32 v64, v64, v175
	v_sub_f32_e32 v65, v65, v175
	v_sub_f32_e32 v66, v66, v175
	v_sub_f32_e32 v67, v67, v175
	v_sub_f32_e32 v68, v68, v175
	v_sub_f32_e32 v69, v69, v175
	v_sub_f32_e32 v70, v70, v175
	v_sub_f32_e32 v71, v71, v175
	v_sub_f32_e32 v72, v72, v175
	v_sub_f32_e32 v73, v73, v175
	v_sub_f32_e32 v74, v74, v175
	v_sub_f32_e32 v75, v75, v175
	v_sub_f32_e32 v76, v76, v175
	v_sub_f32_e32 v77, v77, v175
	v_sub_f32_e32 v78, v78, v175
	v_sub_f32_e32 v79, v79, v175
.Lat_nr_6:
	s_waitcnt vmcnt(2)
	s_barrier
	ds_read_b128 v[196:199], v126 offset:0
	ds_read_b128 v[200:203], v126 offset:512
	ds_read_b128 v[204:207], v126 offset:2048
	ds_read_b128 v[208:211], v126 offset:2560
	ds_read_b128 v[212:215], v126 offset:4096
	ds_read_b128 v[216:219], v126 offset:4608
	ds_read_b64_tr_b16 v[220:221], v139 offset:20480
	ds_read_b64_tr_b16 v[222:223], v139 offset:20992
	ds_read_b64_tr_b16 v[244:245], v139 offset:24576
	ds_read_b64_tr_b16 v[246:247], v139 offset:25088
	s_add_i32 m0, s22, 0x0
	s_cmp_eq_u32 s23, 0
	global_load_lds_dwordx4 v128, s[12:13]
	s_cbranch_scc1 .Lat_k2_7
	s_add_i32 m0, s22, 0x2000
	s_nop 0
	global_load_lds_dwordx4 v129, s[12:13]
.Lat_k2_7:
	s_add_u32 s12, s12, 0x30000
	s_addc_u32 s13, s13, 0
	s_add_i32 m0, s22, 0x18000
	s_nop 0
	global_load_lds_dwordx4 v145, s[14:15]
	s_add_u32 s14, s14, 0x20000
	s_addc_u32 s15, s15, 0
	v_exp_f32_e32 v80, v80
	v_exp_f32_e32 v81, v81
	v_exp_f32_e32 v82, v82
	v_exp_f32_e32 v83, v83
	v_mov_b32_e32 v176, v80
	v_mov_b32_e32 v177, v81
	v_cvt_pk_bf16_f32 v80, v80, v81
	v_add_f32_e32 v176, v82, v176
	v_add_f32_e32 v177, v83, v177
	v_cvt_pk_bf16_f32 v81, v82, v83
	v_exp_f32_e32 v84, v84
	v_exp_f32_e32 v85, v85
	s_waitcnt lgkmcnt(8)
	v_mfma_f32_32x32x16_bf16 v[48:63], v[196:199], v[110:113], v[224:239]
	ds_read_b128 v[196:199], v126 offset:6144
	ds_read_b64_tr_b16 v[240:241], v139 offset:21504
	ds_read_b64_tr_b16 v[242:243], v139 offset:22016
	v_exp_f32_e32 v86, v86
	v_exp_f32_e32 v87, v87
	v_add_f32_e32 v176, v84, v176
	v_add_f32_e32 v177, v85, v177
	v_mfma_f32_32x32x16_bf16 v[32:47], v[200:203], v[110:113], v[224:239]
	ds_read_b128 v[200:203], v126 offset:6656
	ds_read_b64_tr_b16 v[122:123], v139 offset:25600
	ds_read_b64_tr_b16 v[124:125], v139 offset:26112
	v_cvt_pk_bf16_f32 v82, v84, v85
	v_add_f32_e32 v176, v86, v176
	v_add_f32_e32 v177, v87, v177
	v_cvt_pk_bf16_f32 v83, v86, v87
	s_waitcnt lgkmcnt(12)
	v_mfma_f32_32x32x16_bf16 v[48:63], v[204:207], v[106:109], v[48:63]
	ds_read_b128 v[204:207], v126 offset:8192
	v_exp_f32_e32 v88, v88
	v_exp_f32_e32 v89, v89
	v_exp_f32_e32 v90, v90
	v_exp_f32_e32 v91, v91
	v_mfma_f32_32x32x16_bf16 v[32:47], v[208:211], v[106:109], v[32:47]
	ds_read_b128 v[208:211], v126 offset:8704
	v_add_f32_e32 v176, v88, v176
	v_add_f32_e32 v177, v89, v177
	v_cvt_pk_bf16_f32 v84, v88, v89
	v_add_f32_e32 v176, v90, v176
	s_waitcnt lgkmcnt(12)
	v_mfma_f32_32x32x16_bf16 v[48:63], v[212:215], v[114:117], v[48:63]
	ds_read_b128 v[212:215], v126 offset:10240
	v_add_f32_e32 v177, v91, v177
	v_cvt_pk_bf16_f32 v85, v90, v91
	v_exp_f32_e32 v92, v92
	v_exp_f32_e32 v93, v93
	s_waitcnt lgkmcnt(9)
	v_mfma_f32_32x32x16_bf16 v[0:15], v[80:83], v[220:223], v[0:15]
	ds_read_b64_tr_b16 v[220:221], v139 offset:22528
	ds_read_b64_tr_b16 v[222:223], v139 offset:23040
	v_exp_f32_e32 v94, v94
	v_exp_f32_e32 v95, v95
	v_add_f32_e32 v176, v92, v176
	v_add_f32_e32 v177, v93, v177
	v_mfma_f32_32x32x16_bf16 v[16:31], v[80:83], v[244:247], v[16:31]
	ds_read_b64_tr_b16 v[244:245], v139 offset:26624
	ds_read_b64_tr_b16 v[246:247], v139 offset:27136
	v_cvt_pk_bf16_f32 v86, v92, v93
	v_add_f32_e32 v176, v94, v176
	v_add_f32_e32 v177, v95, v177
	v_cvt_pk_bf16_f32 v87, v94, v95
	v_mfma_f32_32x32x16_bf16 v[32:47], v[216:219], v[114:117], v[32:47]
	ds_read_b128 v[216:219], v126 offset:10752
	v_exp_f32_e32 v64, v64
	v_exp_f32_e32 v65, v65
	v_exp_f32_e32 v66, v66
	v_exp_f32_e32 v67, v67
	s_waitcnt lgkmcnt(10)
	v_mfma_f32_32x32x16_bf16 v[48:63], v[196:199], v[118:121], v[48:63]
	v_add_f32_e32 v176, v64, v176
	v_add_f32_e32 v177, v65, v177
	v_cvt_pk_bf16_f32 v64, v64, v65
	v_add_f32_e32 v176, v66, v176
	v_mfma_f32_32x32x16_bf16 v[32:47], v[200:203], v[118:121], v[32:47]
	v_add_f32_e32 v177, v67, v177
	v_cvt_pk_bf16_f32 v65, v66, v67
	v_exp_f32_e32 v68, v68
	v_exp_f32_e32 v69, v69
	s_waitcnt lgkmcnt(8)
	v_mfma_f32_32x32x16_bf16 v[0:15], v[84:87], v[240:243], v[0:15]
	ds_read_b64_tr_b16 v[240:241], v139 offset:23552
	ds_read_b64_tr_b16 v[242:243], v139 offset:24064
	v_exp_f32_e32 v70, v70
	v_exp_f32_e32 v71, v71
	v_add_f32_e32 v176, v68, v176
	v_add_f32_e32 v177, v69, v177
	v_mfma_f32_32x32x16_bf16 v[16:31], v[84:87], v[122:125], v[16:31]
	ds_read_b64_tr_b16 v[122:123], v139 offset:27648
	ds_read_b64_tr_b16 v[124:125], v139 offset:28160
	v_cvt_pk_bf16_f32 v66, v68, v69
	v_add_f32_e32 v176, v70, v176
	v_add_f32_e32 v177, v71, v177
	v_cvt_pk_bf16_f32 v67, v70, v71
	s_waitcnt lgkmcnt(10)
	v_mfma_f32_32x32x16_bf16 v[48:63], v[204:207], v[102:105], v[48:63]
	v_exp_f32_e32 v72, v72
	v_exp_f32_e32 v73, v73
	v_exp_f32_e32 v74, v74
	v_exp_f32_e32 v75, v75
	v_mfma_f32_32x32x16_bf16 v[32:47], v[208:211], v[102:105], v[32:47]
	v_add_f32_e32 v176, v72, v176
	v_add_f32_e32 v177, v73, v177
	v_cvt_pk_bf16_f32 v68, v72, v73
	v_add_f32_e32 v176, v74, v176
	s_waitcnt lgkmcnt(5)
	v_mfma_f32_32x32x16_bf16 v[0:15], v[64:67], v[220:223], v[0:15]
	v_add_f32_e32 v177, v75, v177
	v_cvt_pk_bf16_f32 v69, v74, v75
	v_exp_f32_e32 v76, v76
	v_exp_f32_e32 v77, v77
	v_mfma_f32_32x32x16_bf16 v[16:31], v[64:67], v[244:247], v[16:31]
	v_exp_f32_e32 v78, v78
	v_exp_f32_e32 v79, v79
	v_add_f32_e32 v176, v76, v176
	v_add_f32_e32 v177, v77, v177
	s_waitcnt lgkmcnt(4)
	v_mfma_f32_32x32x16_bf16 v[48:63], v[212:215], v[98:101], v[48:63]
	v_cvt_pk_bf16_f32 v70, v76, v77
	v_add_f32_e32 v176, v78, v176
	v_add_f32_e32 v177, v79, v177
	v_cvt_pk_bf16_f32 v71, v78, v79
	v_mfma_f32_32x32x16_bf16 v[32:47], v[216:219], v[98:101], v[32:47]
	v_add_f32_e32 v175, v176, v177
	v_mov_b32_e32 v178, v175
	v_add_f32_e32 v147, v147, v175
	s_nop 0
	s_waitcnt lgkmcnt(0)
	v_mfma_f32_32x32x16_bf16 v[0:15], v[68:71], v[240:243], v[0:15]
	v_permlane32_swap_b32_e32 v175, v178
	v_add_f32_e32 v175, v175, v178
	v_cmp_lt_f32_e32 vcc, 0x43800000, v175
	v_mfma_f32_32x32x16_bf16 v[16:31], v[68:71], v[122:125], v[16:31]
	s_cbranch_vccz .Lat_nr_8
	v_log_f32_e32 v175, v175
	s_nop 0
	v_max_f32_e32 v175, 0, v175
	v_exp_f32_e64 v178, -v175
	s_and_saveexec_b64 s[4:5], s[2:3]
	ds_write_b32 v143, v178 offset:40960
	s_or_b64 exec, exec, s[4:5]
	s_waitcnt lgkmcnt(0)
	v_add_u32_e32 v179, s33, v191
	v_sub_f32_e32 v224, v224, v175
	v_mul_f32_e32 v147, v147, v178
	ds_read_b128 v[196:199], v179 offset:40960
	ds_read_b128 v[200:203], v179 offset:40992
	ds_read_b128 v[204:207], v179 offset:41024
	ds_read_b128 v[208:211], v179 offset:41056
	s_waitcnt lgkmcnt(0)
	s_nop 15
	v_pk_mul_f32 v[0:1], v[0:1], v[196:197]
	v_pk_mul_f32 v[2:3], v[2:3], v[198:199]
	v_pk_mul_f32 v[4:5], v[4:5], v[200:201]
	v_pk_mul_f32 v[6:7], v[6:7], v[202:203]
	v_pk_mul_f32 v[8:9], v[8:9], v[204:205]
	v_pk_mul_f32 v[10:11], v[10:11], v[206:207]
	v_pk_mul_f32 v[12:13], v[12:13], v[208:209]
	v_pk_mul_f32 v[14:15], v[14:15], v[210:211]
	v_pk_mul_f32 v[16:17], v[16:17], v[196:197]
	v_pk_mul_f32 v[18:19], v[18:19], v[198:199]
	v_pk_mul_f32 v[20:21], v[20:21], v[200:201]
	v_pk_mul_f32 v[22:23], v[22:23], v[202:203]
	v_pk_mul_f32 v[24:25], v[24:25], v[204:205]
	v_pk_mul_f32 v[26:27], v[26:27], v[206:207]
	v_pk_mul_f32 v[28:29], v[28:29], v[208:209]
	v_pk_mul_f32 v[30:31], v[30:31], v[210:211]
	v_mov_b32_e32 v225, v224
	v_mov_b32_e32 v226, v224
	v_mov_b32_e32 v227, v224
	v_mov_b32_e32 v228, v224
	v_mov_b32_e32 v229, v224
	v_mov_b32_e32 v230, v224
	v_mov_b32_e32 v231, v224
	v_mov_b32_e32 v232, v224
	v_mov_b32_e32 v233, v224
	v_mov_b32_e32 v234, v224
	v_mov_b32_e32 v235, v224
	v_mov_b32_e32 v236, v224
	v_mov_b32_e32 v237, v224
	v_mov_b32_e32 v238, v224
	v_mov_b32_e32 v239, v224
	v_sub_f32_e32 v48, v48, v175
	v_sub_f32_e32 v49, v49, v175
	v_sub_f32_e32 v50, v50, v175
	v_sub_f32_e32 v51, v51, v175
	v_sub_f32_e32 v52, v52, v175
	v_sub_f32_e32 v53, v53, v175
	v_sub_f32_e32 v54, v54, v175
	v_sub_f32_e32 v55, v55, v175
	v_sub_f32_e32 v56, v56, v175
	v_sub_f32_e32 v57, v57, v175
	v_sub_f32_e32 v58, v58, v175
	v_sub_f32_e32 v59, v59, v175
	v_sub_f32_e32 v60, v60, v175
	v_sub_f32_e32 v61, v61, v175
	v_sub_f32_e32 v62, v62, v175
	v_sub_f32_e32 v63, v63, v175
	v_sub_f32_e32 v32, v32, v175
	v_sub_f32_e32 v33, v33, v175
	v_sub_f32_e32 v34, v34, v175
	v_sub_f32_e32 v35, v35, v175
	v_sub_f32_e32 v36, v36, v175
	v_sub_f32_e32 v37, v37, v175
	v_sub_f32_e32 v38, v38, v175
	v_sub_f32_e32 v39, v39, v175
	v_sub_f32_e32 v40, v40, v175
	v_sub_f32_e32 v41, v41, v175
	v_sub_f32_e32 v42, v42, v175
	v_sub_f32_e32 v43, v43, v175
	v_sub_f32_e32 v44, v44, v175
	v_sub_f32_e32 v45, v45, v175
	v_sub_f32_e32 v46, v46, v175
	v_sub_f32_e32 v47, v47, v175
.Lat_nr_8:
	s_waitcnt vmcnt(2)
	s_barrier
	ds_read_b128 v[196:199], v126 offset:20480
	ds_read_b128 v[200:203], v126 offset:20992
	ds_read_b128 v[204:207], v126 offset:22528
	ds_read_b128 v[208:211], v126 offset:23040
	ds_read_b128 v[212:215], v126 offset:24576
	ds_read_b128 v[216:219], v126 offset:25088
	ds_read_b64_tr_b16 v[220:221], v127 offset:0
	ds_read_b64_tr_b16 v[222:223], v127 offset:512
	ds_read_b64_tr_b16 v[244:245], v127 offset:4096
	ds_read_b64_tr_b16 v[246:247], v127 offset:4608
	s_add_i32 m0, s22, 0x5000
	s_cmp_eq_u32 s23, 0
	global_load_lds_dwordx4 v128, s[12:13]
	s_cbranch_scc1 .Lat_k2_9
	s_add_i32 m0, s22, 0x7000
	s_nop 0
	global_load_lds_dwordx4 v129, s[12:13]
.Lat_k2_9:
	s_add_u32 s12, s12, 0x30000
	s_addc_u32 s13, s13, 0
	s_add_i32 m0, s22, 0x3000
	s_nop 0
	global_load_lds_dwordx4 v145, s[14:15]
	s_add_u32 s14, s14, 0x20000
	s_addc_u32 s15, s15, 0
	v_exp_f32_e32 v48, v48
	v_exp_f32_e32 v49, v49
	v_exp_f32_e32 v50, v50
	v_exp_f32_e32 v51, v51
	v_mov_b32_e32 v176, v48
	v_mov_b32_e32 v177, v49
	v_cvt_pk_bf16_f32 v48, v48, v49
	v_add_f32_e32 v176, v50, v176
	v_add_f32_e32 v177, v51, v177
	v_cvt_pk_bf16_f32 v49, v50, v51
	v_exp_f32_e32 v52, v52
	v_exp_f32_e32 v53, v53
	s_waitcnt lgkmcnt(8)
	v_mfma_f32_32x32x16_bf16 v[80:95], v[196:199], v[110:113], v[224:239]
	ds_read_b128 v[196:199], v126 offset:26624
	ds_read_b64_tr_b16 v[240:241], v127 offset:1024
	ds_read_b64_tr_b16 v[242:243], v127 offset:1536
	v_exp_f32_e32 v54, v54
	v_exp_f32_e32 v55, v55
	v_add_f32_e32 v176, v52, v176
	v_add_f32_e32 v177, v53, v177
	v_mfma_f32_32x32x16_bf16 v[64:79], v[200:203], v[110:113], v[224:239]
	ds_read_b128 v[200:203], v126 offset:27136
	ds_read_b64_tr_b16 v[122:123], v127 offset:5120
	ds_read_b64_tr_b16 v[124:125], v127 offset:5632
	v_cvt_pk_bf16_f32 v50, v52, v53
	v_add_f32_e32 v176, v54, v176
	v_add_f32_e32 v177, v55, v177
	v_cvt_pk_bf16_f32 v51, v54, v55
	s_waitcnt lgkmcnt(12)
	v_mfma_f32_32x32x16_bf16 v[80:95], v[204:207], v[106:109], v[80:95]
	ds_read_b128 v[204:207], v126 offset:28672
	v_exp_f32_e32 v56, v56
	v_exp_f32_e32 v57, v57
	v_exp_f32_e32 v58, v58
	v_exp_f32_e32 v59, v59
	v_mfma_f32_32x32x16_bf16 v[64:79], v[208:211], v[106:109], v[64:79]
	ds_read_b128 v[208:211], v126 offset:29184
	v_add_f32_e32 v176, v56, v176
	v_add_f32_e32 v177, v57, v177
	v_cvt_pk_bf16_f32 v52, v56, v57
	v_add_f32_e32 v176, v58, v176
	s_waitcnt lgkmcnt(12)
	v_mfma_f32_32x32x16_bf16 v[80:95], v[212:215], v[114:117], v[80:95]
	ds_read_b128 v[212:215], v126 offset:30720
	v_add_f32_e32 v177, v59, v177
	v_cvt_pk_bf16_f32 v53, v58, v59
	v_exp_f32_e32 v60, v60
	v_exp_f32_e32 v61, v61
	s_waitcnt lgkmcnt(9)
	v_mfma_f32_32x32x16_bf16 v[0:15], v[48:51], v[220:223], v[0:15]
	ds_read_b64_tr_b16 v[220:221], v127 offset:2048
	ds_read_b64_tr_b16 v[222:223], v127 offset:2560
	v_exp_f32_e32 v62, v62
	v_exp_f32_e32 v63, v63
	v_add_f32_e32 v176, v60, v176
	v_add_f32_e32 v177, v61, v177
	v_mfma_f32_32x32x16_bf16 v[16:31], v[48:51], v[244:247], v[16:31]
	ds_read_b64_tr_b16 v[244:245], v127 offset:6144
	ds_read_b64_tr_b16 v[246:247], v127 offset:6656
	v_cvt_pk_bf16_f32 v54, v60, v61
	v_add_f32_e32 v176, v62, v176
	v_add_f32_e32 v177, v63, v177
	v_cvt_pk_bf16_f32 v55, v62, v63
	v_mfma_f32_32x32x16_bf16 v[64:79], v[216:219], v[114:117], v[64:79]
	ds_read_b128 v[216:219], v126 offset:31232
	v_exp_f32_e32 v32, v32
	v_exp_f32_e32 v33, v33
	v_exp_f32_e32 v34, v34
	v_exp_f32_e32 v35, v35
	s_waitcnt lgkmcnt(10)
	v_mfma_f32_32x32x16_bf16 v[80:95], v[196:199], v[118:121], v[80:95]
	v_add_f32_e32 v176, v32, v176
	v_add_f32_e32 v177, v33, v177
	v_cvt_pk_bf16_f32 v32, v32, v33
	v_add_f32_e32 v176, v34, v176
	v_mfma_f32_32x32x16_bf16 v[64:79], v[200:203], v[118:121], v[64:79]
	v_add_f32_e32 v177, v35, v177
	v_cvt_pk_bf16_f32 v33, v34, v35
	v_exp_f32_e32 v36, v36
	v_exp_f32_e32 v37, v37
	s_waitcnt lgkmcnt(8)
	v_mfma_f32_32x32x16_bf16 v[0:15], v[52:55], v[240:243], v[0:15]
	ds_read_b64_tr_b16 v[240:241], v127 offset:3072
	ds_read_b64_tr_b16 v[242:243], v127 offset:3584
	v_exp_f32_e32 v38, v38
	v_exp_f32_e32 v39, v39
	v_add_f32_e32 v176, v36, v176
	v_add_f32_e32 v177, v37, v177
	v_mfma_f32_32x32x16_bf16 v[16:31], v[52:55], v[122:125], v[16:31]
	ds_read_b64_tr_b16 v[122:123], v127 offset:7168
	ds_read_b64_tr_b16 v[124:125], v127 offset:7680
	v_cvt_pk_bf16_f32 v34, v36, v37
	v_add_f32_e32 v176, v38, v176
	v_add_f32_e32 v177, v39, v177
	v_cvt_pk_bf16_f32 v35, v38, v39
	s_waitcnt lgkmcnt(10)
	v_mfma_f32_32x32x16_bf16 v[80:95], v[204:207], v[102:105], v[80:95]
	v_exp_f32_e32 v40, v40
	v_exp_f32_e32 v41, v41
	v_exp_f32_e32 v42, v42
	v_exp_f32_e32 v43, v43
	v_mfma_f32_32x32x16_bf16 v[64:79], v[208:211], v[102:105], v[64:79]
	v_add_f32_e32 v176, v40, v176
	v_add_f32_e32 v177, v41, v177
	v_cvt_pk_bf16_f32 v36, v40, v41
	v_add_f32_e32 v176, v42, v176
	s_waitcnt lgkmcnt(5)
	v_mfma_f32_32x32x16_bf16 v[0:15], v[32:35], v[220:223], v[0:15]
	v_add_f32_e32 v177, v43, v177
	v_cvt_pk_bf16_f32 v37, v42, v43
	v_exp_f32_e32 v44, v44
	v_exp_f32_e32 v45, v45
	v_mfma_f32_32x32x16_bf16 v[16:31], v[32:35], v[244:247], v[16:31]
	v_exp_f32_e32 v46, v46
	v_exp_f32_e32 v47, v47
	v_add_f32_e32 v176, v44, v176
	v_add_f32_e32 v177, v45, v177
	s_waitcnt lgkmcnt(4)
	v_mfma_f32_32x32x16_bf16 v[80:95], v[212:215], v[98:101], v[80:95]
	v_cvt_pk_bf16_f32 v38, v44, v45
	v_add_f32_e32 v176, v46, v176
	v_add_f32_e32 v177, v47, v177
	v_cvt_pk_bf16_f32 v39, v46, v47
	v_mfma_f32_32x32x16_bf16 v[64:79], v[216:219], v[98:101], v[64:79]
	v_add_f32_e32 v175, v176, v177
	v_mov_b32_e32 v178, v175
	v_add_f32_e32 v147, v147, v175
	s_nop 0
	s_waitcnt lgkmcnt(0)
	v_mfma_f32_32x32x16_bf16 v[0:15], v[36:39], v[240:243], v[0:15]
	v_permlane32_swap_b32_e32 v175, v178
	v_add_f32_e32 v175, v175, v178
	v_cmp_lt_f32_e32 vcc, 0x43800000, v175
	v_mfma_f32_32x32x16_bf16 v[16:31], v[36:39], v[122:125], v[16:31]
	s_cbranch_vccz .Lat_nr_10
	v_log_f32_e32 v175, v175
	s_nop 0
	v_max_f32_e32 v175, 0, v175
	v_exp_f32_e64 v178, -v175
	s_and_saveexec_b64 s[4:5], s[2:3]
	ds_write_b32 v143, v178 offset:40960
	s_or_b64 exec, exec, s[4:5]
	s_waitcnt lgkmcnt(0)
	v_add_u32_e32 v179, s33, v191
	v_sub_f32_e32 v224, v224, v175
	v_mul_f32_e32 v147, v147, v178
	ds_read_b128 v[196:199], v179 offset:40960
	ds_read_b128 v[200:203], v179 offset:40992
	ds_read_b128 v[204:207], v179 offset:41024
	ds_read_b128 v[208:211], v179 offset:41056
	s_waitcnt lgkmcnt(0)
	s_nop 15
	v_pk_mul_f32 v[0:1], v[0:1], v[196:197]
	v_pk_mul_f32 v[2:3], v[2:3], v[198:199]
	v_pk_mul_f32 v[4:5], v[4:5], v[200:201]
	v_pk_mul_f32 v[6:7], v[6:7], v[202:203]
	v_pk_mul_f32 v[8:9], v[8:9], v[204:205]
	v_pk_mul_f32 v[10:11], v[10:11], v[206:207]
	v_pk_mul_f32 v[12:13], v[12:13], v[208:209]
	v_pk_mul_f32 v[14:15], v[14:15], v[210:211]
	v_pk_mul_f32 v[16:17], v[16:17], v[196:197]
	v_pk_mul_f32 v[18:19], v[18:19], v[198:199]
	v_pk_mul_f32 v[20:21], v[20:21], v[200:201]
	v_pk_mul_f32 v[22:23], v[22:23], v[202:203]
	v_pk_mul_f32 v[24:25], v[24:25], v[204:205]
	v_pk_mul_f32 v[26:27], v[26:27], v[206:207]
	v_pk_mul_f32 v[28:29], v[28:29], v[208:209]
	v_pk_mul_f32 v[30:31], v[30:31], v[210:211]
	v_mov_b32_e32 v225, v224
	v_mov_b32_e32 v226, v224
	v_mov_b32_e32 v227, v224
	v_mov_b32_e32 v228, v224
	v_mov_b32_e32 v229, v224
	v_mov_b32_e32 v230, v224
	v_mov_b32_e32 v231, v224
	v_mov_b32_e32 v232, v224
	v_mov_b32_e32 v233, v224
	v_mov_b32_e32 v234, v224
	v_mov_b32_e32 v235, v224
	v_mov_b32_e32 v236, v224
	v_mov_b32_e32 v237, v224
	v_mov_b32_e32 v238, v224
	v_mov_b32_e32 v239, v224
	v_sub_f32_e32 v80, v80, v175
	v_sub_f32_e32 v81, v81, v175
	v_sub_f32_e32 v82, v82, v175
	v_sub_f32_e32 v83, v83, v175
	v_sub_f32_e32 v84, v84, v175
	v_sub_f32_e32 v85, v85, v175
	v_sub_f32_e32 v86, v86, v175
	v_sub_f32_e32 v87, v87, v175
	v_sub_f32_e32 v88, v88, v175
	v_sub_f32_e32 v89, v89, v175
	v_sub_f32_e32 v90, v90, v175
	v_sub_f32_e32 v91, v91, v175
	v_sub_f32_e32 v92, v92, v175
	v_sub_f32_e32 v93, v93, v175
	v_sub_f32_e32 v94, v94, v175
	v_sub_f32_e32 v95, v95, v175
	v_sub_f32_e32 v64, v64, v175
	v_sub_f32_e32 v65, v65, v175
	v_sub_f32_e32 v66, v66, v175
	v_sub_f32_e32 v67, v67, v175
	v_sub_f32_e32 v68, v68, v175
	v_sub_f32_e32 v69, v69, v175
	v_sub_f32_e32 v70, v70, v175
	v_sub_f32_e32 v71, v71, v175
	v_sub_f32_e32 v72, v72, v175
	v_sub_f32_e32 v73, v73, v175
	v_sub_f32_e32 v74, v74, v175
	v_sub_f32_e32 v75, v75, v175
	v_sub_f32_e32 v76, v76, v175
	v_sub_f32_e32 v77, v77, v175
	v_sub_f32_e32 v78, v78, v175
	v_sub_f32_e32 v79, v79, v175
.Lat_nr_10:
	s_waitcnt vmcnt(2)
	s_barrier
	ds_read_b128 v[196:199], v194 offset:0
	ds_read_b128 v[200:203], v194 offset:512
	ds_read_b128 v[204:207], v194 offset:2048
	ds_read_b128 v[208:211], v194 offset:2560
	ds_read_b128 v[212:215], v194 offset:4096
	ds_read_b128 v[216:219], v194 offset:4608
	ds_read_b64_tr_b16 v[220:221], v127 offset:20480
	ds_read_b64_tr_b16 v[222:223], v127 offset:20992
	ds_read_b64_tr_b16 v[244:245], v127 offset:24576
	ds_read_b64_tr_b16 v[246:247], v127 offset:25088
	s_add_i32 m0, s22, 0x10000
	s_cmp_eq_u32 s23, 0
	global_load_lds_dwordx4 v128, s[12:13]
	s_cbranch_scc1 .Lat_k2_11
	s_add_i32 m0, s22, 0x12000
	s_nop 0
	global_load_lds_dwordx4 v129, s[12:13]
.Lat_k2_11:
	s_add_u32 s12, s12, 0x30000
	s_addc_u32 s13, s13, 0
	s_add_i32 m0, s22, 0x8000
	s_nop 0
	global_load_lds_dwordx4 v145, s[14:15]
	s_add_u32 s14, s14, 0x20000
	s_addc_u32 s15, s15, 0
	v_exp_f32_e32 v80, v80
	v_exp_f32_e32 v81, v81
	v_exp_f32_e32 v82, v82
	v_exp_f32_e32 v83, v83
	v_mov_b32_e32 v176, v80
	v_mov_b32_e32 v177, v81
	v_cvt_pk_bf16_f32 v80, v80, v81
	v_add_f32_e32 v176, v82, v176
	v_add_f32_e32 v177, v83, v177
	v_cvt_pk_bf16_f32 v81, v82, v83
	v_exp_f32_e32 v84, v84
	v_exp_f32_e32 v85, v85
	s_waitcnt lgkmcnt(8)
	v_mfma_f32_32x32x16_bf16 v[48:63], v[196:199], v[110:113], v[224:239]
	ds_read_b128 v[196:199], v194 offset:6144
	ds_read_b64_tr_b16 v[240:241], v127 offset:21504
	ds_read_b64_tr_b16 v[242:243], v127 offset:22016
	v_exp_f32_e32 v86, v86
	v_exp_f32_e32 v87, v87
	v_add_f32_e32 v176, v84, v176
	v_add_f32_e32 v177, v85, v177
	v_mfma_f32_32x32x16_bf16 v[32:47], v[200:203], v[110:113], v[224:239]
	ds_read_b128 v[200:203], v194 offset:6656
	ds_read_b64_tr_b16 v[122:123], v127 offset:25600
	ds_read_b64_tr_b16 v[124:125], v127 offset:26112
	v_cvt_pk_bf16_f32 v82, v84, v85
	v_add_f32_e32 v176, v86, v176
	v_add_f32_e32 v177, v87, v177
	v_cvt_pk_bf16_f32 v83, v86, v87
	s_waitcnt lgkmcnt(12)
	v_mfma_f32_32x32x16_bf16 v[48:63], v[204:207], v[106:109], v[48:63]
	ds_read_b128 v[204:207], v194 offset:8192
	v_exp_f32_e32 v88, v88
	v_exp_f32_e32 v89, v89
	v_exp_f32_e32 v90, v90
	v_exp_f32_e32 v91, v91
	v_mfma_f32_32x32x16_bf16 v[32:47], v[208:211], v[106:109], v[32:47]
	ds_read_b128 v[208:211], v194 offset:8704
	v_add_f32_e32 v176, v88, v176
	v_add_f32_e32 v177, v89, v177
	v_cvt_pk_bf16_f32 v84, v88, v89
	v_add_f32_e32 v176, v90, v176
	s_waitcnt lgkmcnt(12)
	v_mfma_f32_32x32x16_bf16 v[48:63], v[212:215], v[114:117], v[48:63]
	ds_read_b128 v[212:215], v194 offset:10240
	v_add_f32_e32 v177, v91, v177
	v_cvt_pk_bf16_f32 v85, v90, v91
	v_exp_f32_e32 v92, v92
	v_exp_f32_e32 v93, v93
	s_waitcnt lgkmcnt(9)
	v_mfma_f32_32x32x16_bf16 v[0:15], v[80:83], v[220:223], v[0:15]
	ds_read_b64_tr_b16 v[220:221], v127 offset:22528
	ds_read_b64_tr_b16 v[222:223], v127 offset:23040
	v_exp_f32_e32 v94, v94
	v_exp_f32_e32 v95, v95
	v_add_f32_e32 v176, v92, v176
	v_add_f32_e32 v177, v93, v177
	v_mfma_f32_32x32x16_bf16 v[16:31], v[80:83], v[244:247], v[16:31]
	ds_read_b64_tr_b16 v[244:245], v127 offset:26624
	ds_read_b64_tr_b16 v[246:247], v127 offset:27136
	v_cvt_pk_bf16_f32 v86, v92, v93
	v_add_f32_e32 v176, v94, v176
	v_add_f32_e32 v177, v95, v177
	v_cvt_pk_bf16_f32 v87, v94, v95
	v_mfma_f32_32x32x16_bf16 v[32:47], v[216:219], v[114:117], v[32:47]
	ds_read_b128 v[216:219], v194 offset:10752
	v_exp_f32_e32 v64, v64
	v_exp_f32_e32 v65, v65
	v_exp_f32_e32 v66, v66
	v_exp_f32_e32 v67, v67
	s_waitcnt lgkmcnt(10)
; DEV float max3f(float a, float b, float c) { return fmaxf(fmaxf(a, b), c); }
; #define LOADK(t) do { const long kb_ = KBASE(t); kreg0 = *(const u32x4*)(K + (kb_ + lane) * 1536 + h * 96 + wid * 8); \
;         if (k2) kreg1 = *(const u32x4*)(K + (kb_ + lane) * 1536 + h * 96 + (8 + wid) * 8); } while (0)
; #define LOADV(t) do { const long kb_ = KBASE(t); vreg = *(const u32x4*)(V + (kb_ + 16 * (wid & 3) + (lane >> 2)) * 1024 + h * 64 + (wid >> 2) * 32 + (lane & 3) * 8); } while (0)
; #define STOREK(s) do { LAS unsigned char* st_ = sh + (s) * STG; *(LAS u32x4*)(st_ + wid * 1024 + lane * 16) = kreg0; if (k2) *(LAS u32x4*)(st_ + (8 + wid) * 1024 + lane * 16) = kreg1; } while (0)
; #define STOREV(s) do { LAS unsigned char* st_ = sh + (s) * STG; *(LAS u32x4*)(st_ + KST + wid * 1024 + lane * 16) = vreg; } while (0)
; DEV void attn_unit(int b, int h, int qb, const bf16_t* Q, const bf16_t* K, const bf16_t* V, bf16_t* O, LAS unsigned char* sh, const int tid, const float* qgain) {
;     ...
;     LOADK(0); LOADV(0); STOREK(0); STOREV(0); LOADK(1); STOREK(1); __syncthreads();
;     f32x16 pA0, pA1, pB0 = f32x16{}, pB1 = f32x16{};
;     QKT(pA0, pA1, 0);
;     { float m0 = pA0[0];
; #pragma unroll
;         for (int r = 0; r < 16; ++r) m0 = max3f(m0, pA0[r], pA1[r]);
;         mrun = fmaxf(m0, __shfl_xor(m0, 32)); }
;     for (int t = 0; t < NT - 2; t += 2) {
;         STEP(pA0, pA1, pB0, pB1, t, true);
;         STEP(pB0, pB1, pA0, pA1, t + 1, true);
;     }
	v_mfma_f32_32x32x16_bf16 v[48:63], v[196:199], v[118:121], v[48:63]
	v_add_f32_e32 v176, v64, v176
	v_add_f32_e32 v177, v65, v177
	v_cvt_pk_bf16_f32 v64, v64, v65
	v_add_f32_e32 v176, v66, v176
	v_mfma_f32_32x32x16_bf16 v[32:47], v[200:203], v[118:121], v[32:47]
	v_add_f32_e32 v177, v67, v177
	v_cvt_pk_bf16_f32 v65, v66, v67
	v_exp_f32_e32 v68, v68
	v_exp_f32_e32 v69, v69
	s_waitcnt lgkmcnt(8)
	v_mfma_f32_32x32x16_bf16 v[0:15], v[84:87], v[240:243], v[0:15]
	ds_read_b64_tr_b16 v[240:241], v127 offset:23552
	ds_read_b64_tr_b16 v[242:243], v127 offset:24064
	v_exp_f32_e32 v70, v70
	v_exp_f32_e32 v71, v71
	v_add_f32_e32 v176, v68, v176
	v_add_f32_e32 v177, v69, v177
	v_mfma_f32_32x32x16_bf16 v[16:31], v[84:87], v[122:125], v[16:31]
	ds_read_b64_tr_b16 v[122:123], v127 offset:27648
	ds_read_b64_tr_b16 v[124:125], v127 offset:28160
	v_cvt_pk_bf16_f32 v66, v68, v69
	v_add_f32_e32 v176, v70, v176
	v_add_f32_e32 v177, v71, v177
	v_cvt_pk_bf16_f32 v67, v70, v71
	s_waitcnt lgkmcnt(10)
	v_mfma_f32_32x32x16_bf16 v[48:63], v[204:207], v[102:105], v[48:63]
	v_exp_f32_e32 v72, v72
	v_exp_f32_e32 v73, v73
	v_exp_f32_e32 v74, v74
	v_exp_f32_e32 v75, v75
	v_mfma_f32_32x32x16_bf16 v[32:47], v[208:211], v[102:105], v[32:47]
	v_add_f32_e32 v176, v72, v176
	v_add_f32_e32 v177, v73, v177
	v_cvt_pk_bf16_f32 v68, v72, v73
	v_add_f32_e32 v176, v74, v176
	s_waitcnt lgkmcnt(5)
	v_mfma_f32_32x32x16_bf16 v[0:15], v[64:67], v[220:223], v[0:15]
	v_add_f32_e32 v177, v75, v177
	v_cvt_pk_bf16_f32 v69, v74, v75
	v_exp_f32_e32 v76, v76
	v_exp_f32_e32 v77, v77
	v_mfma_f32_32x32x16_bf16 v[16:31], v[64:67], v[244:247], v[16:31]
	v_exp_f32_e32 v78, v78
	v_exp_f32_e32 v79, v79
	v_add_f32_e32 v176, v76, v176
	v_add_f32_e32 v177, v77, v177
	s_waitcnt lgkmcnt(4)
	v_mfma_f32_32x32x16_bf16 v[48:63], v[212:215], v[98:101], v[48:63]
	v_cvt_pk_bf16_f32 v70, v76, v77
	v_add_f32_e32 v176, v78, v176
	v_add_f32_e32 v177, v79, v177
	v_cvt_pk_bf16_f32 v71, v78, v79
	v_mfma_f32_32x32x16_bf16 v[32:47], v[216:219], v[98:101], v[32:47]
	v_add_f32_e32 v175, v176, v177
	v_mov_b32_e32 v178, v175
	v_add_f32_e32 v147, v147, v175
	s_nop 0
	s_waitcnt lgkmcnt(0)
	v_mfma_f32_32x32x16_bf16 v[0:15], v[68:71], v[240:243], v[0:15]
	v_permlane32_swap_b32_e32 v175, v178
	v_add_f32_e32 v175, v175, v178
	v_cmp_lt_f32_e32 vcc, 0x43800000, v175
	v_mfma_f32_32x32x16_bf16 v[16:31], v[68:71], v[122:125], v[16:31]
	s_cbranch_vccz .Lat_nr_12
	v_log_f32_e32 v175, v175
	s_nop 0
	v_max_f32_e32 v175, 0, v175
	v_exp_f32_e64 v178, -v175
	s_and_saveexec_b64 s[4:5], s[2:3]
	ds_write_b32 v143, v178 offset:40960
	s_or_b64 exec, exec, s[4:5]
	s_waitcnt lgkmcnt(0)
	v_add_u32_e32 v179, s33, v191
	v_sub_f32_e32 v224, v224, v175
	v_mul_f32_e32 v147, v147, v178
	ds_read_b128 v[196:199], v179 offset:40960
	ds_read_b128 v[200:203], v179 offset:40992
	ds_read_b128 v[204:207], v179 offset:41024
	ds_read_b128 v[208:211], v179 offset:41056
	s_waitcnt lgkmcnt(0)
	s_nop 15
	v_pk_mul_f32 v[0:1], v[0:1], v[196:197]
	v_pk_mul_f32 v[2:3], v[2:3], v[198:199]
	v_pk_mul_f32 v[4:5], v[4:5], v[200:201]
	v_pk_mul_f32 v[6:7], v[6:7], v[202:203]
	v_pk_mul_f32 v[8:9], v[8:9], v[204:205]
	v_pk_mul_f32 v[10:11], v[10:11], v[206:207]
	v_pk_mul_f32 v[12:13], v[12:13], v[208:209]
	v_pk_mul_f32 v[14:15], v[14:15], v[210:211]
	v_pk_mul_f32 v[16:17], v[16:17], v[196:197]
	v_pk_mul_f32 v[18:19], v[18:19], v[198:199]
	v_pk_mul_f32 v[20:21], v[20:21], v[200:201]
	v_pk_mul_f32 v[22:23], v[22:23], v[202:203]
	v_pk_mul_f32 v[24:25], v[24:25], v[204:205]
	v_pk_mul_f32 v[26:27], v[26:27], v[206:207]
	v_pk_mul_f32 v[28:29], v[28:29], v[208:209]
	v_pk_mul_f32 v[30:31], v[30:31], v[210:211]
	v_mov_b32_e32 v225, v224
	v_mov_b32_e32 v226, v224
	v_mov_b32_e32 v227, v224
	v_mov_b32_e32 v228, v224
	v_mov_b32_e32 v229, v224
	v_mov_b32_e32 v230, v224
	v_mov_b32_e32 v231, v224
	v_mov_b32_e32 v232, v224
	v_mov_b32_e32 v233, v224
	v_mov_b32_e32 v234, v224
	v_mov_b32_e32 v235, v224
	v_mov_b32_e32 v236, v224
	v_mov_b32_e32 v237, v224
	v_mov_b32_e32 v238, v224
	v_mov_b32_e32 v239, v224
	v_sub_f32_e32 v48, v48, v175
	v_sub_f32_e32 v49, v49, v175
	v_sub_f32_e32 v50, v50, v175
	v_sub_f32_e32 v51, v51, v175
	v_sub_f32_e32 v52, v52, v175
	v_sub_f32_e32 v53, v53, v175
	v_sub_f32_e32 v54, v54, v175
	v_sub_f32_e32 v55, v55, v175
	v_sub_f32_e32 v56, v56, v175
	v_sub_f32_e32 v57, v57, v175
	v_sub_f32_e32 v58, v58, v175
	v_sub_f32_e32 v59, v59, v175
	v_sub_f32_e32 v60, v60, v175
	v_sub_f32_e32 v61, v61, v175
	v_sub_f32_e32 v62, v62, v175
	v_sub_f32_e32 v63, v63, v175
	v_sub_f32_e32 v32, v32, v175
	v_sub_f32_e32 v33, v33, v175
	v_sub_f32_e32 v34, v34, v175
	v_sub_f32_e32 v35, v35, v175
	v_sub_f32_e32 v36, v36, v175
	v_sub_f32_e32 v37, v37, v175
	v_sub_f32_e32 v38, v38, v175
	v_sub_f32_e32 v39, v39, v175
	v_sub_f32_e32 v40, v40, v175
	v_sub_f32_e32 v41, v41, v175
	v_sub_f32_e32 v42, v42, v175
	v_sub_f32_e32 v43, v43, v175
	v_sub_f32_e32 v44, v44, v175
	v_sub_f32_e32 v45, v45, v175
	v_sub_f32_e32 v46, v46, v175
	v_sub_f32_e32 v47, v47, v175
.Lat_nr_12:
	s_waitcnt vmcnt(2)
	s_barrier
	s_sub_u32 s24, s24, 1
	s_cmp_lg_u32 s24, 0
	s_cbranch_scc1 .Lat_loop_4
	ds_read_b128 v[196:199], v194 offset:20480
	ds_read_b128 v[200:203], v194 offset:20992
	ds_read_b128 v[204:207], v194 offset:22528
	ds_read_b128 v[208:211], v194 offset:23040
	ds_read_b128 v[212:215], v194 offset:24576
	ds_read_b128 v[216:219], v194 offset:25088
	ds_read_b64_tr_b16 v[220:221], v139 offset:0
	ds_read_b64_tr_b16 v[222:223], v139 offset:512
	ds_read_b64_tr_b16 v[244:245], v139 offset:4096
	ds_read_b64_tr_b16 v[246:247], v139 offset:4608
	s_add_i32 m0, s22, 0x15000
	s_cmp_eq_u32 s23, 0
	global_load_lds_dwordx4 v128, s[12:13]
	s_cbranch_scc1 .Lat_k2_13
	s_add_i32 m0, s22, 0x17000
	s_nop 0
	global_load_lds_dwordx4 v129, s[12:13]
.Lat_k2_13:
	s_add_i32 m0, s22, 0x13000
	s_nop 0
	global_load_lds_dwordx4 v145, s[14:15]
	s_add_u32 s14, s14, 0x20000
	s_addc_u32 s15, s15, 0
	v_exp_f32_e32 v48, v48
	v_exp_f32_e32 v49, v49
	v_exp_f32_e32 v50, v50
	v_exp_f32_e32 v51, v51
	v_mov_b32_e32 v176, v48
	v_mov_b32_e32 v177, v49
	v_cvt_pk_bf16_f32 v48, v48, v49
	v_add_f32_e32 v176, v50, v176
	v_add_f32_e32 v177, v51, v177
	v_cvt_pk_bf16_f32 v49, v50, v51
	v_exp_f32_e32 v52, v52
	v_exp_f32_e32 v53, v53
	s_waitcnt lgkmcnt(8)
	v_mfma_f32_32x32x16_bf16 v[80:95], v[196:199], v[110:113], v[224:239]
	ds_read_b128 v[196:199], v194 offset:26624
	ds_read_b64_tr_b16 v[240:241], v139 offset:1024
	ds_read_b64_tr_b16 v[242:243], v139 offset:1536
	v_exp_f32_e32 v54, v54
	v_exp_f32_e32 v55, v55
	v_add_f32_e32 v176, v52, v176
	v_add_f32_e32 v177, v53, v177
	v_mfma_f32_32x32x16_bf16 v[64:79], v[200:203], v[110:113], v[224:239]
	ds_read_b128 v[200:203], v194 offset:27136
	ds_read_b64_tr_b16 v[122:123], v139 offset:5120
	ds_read_b64_tr_b16 v[124:125], v139 offset:5632
	v_cvt_pk_bf16_f32 v50, v52, v53
	v_add_f32_e32 v176, v54, v176
	v_add_f32_e32 v177, v55, v177
	v_cvt_pk_bf16_f32 v51, v54, v55
	s_waitcnt lgkmcnt(12)
	v_mfma_f32_32x32x16_bf16 v[80:95], v[204:207], v[106:109], v[80:95]
	ds_read_b128 v[204:207], v194 offset:28672
	v_exp_f32_e32 v56, v56
	v_exp_f32_e32 v57, v57
	v_exp_f32_e32 v58, v58
	v_exp_f32_e32 v59, v59
	v_mfma_f32_32x32x16_bf16 v[64:79], v[208:211], v[106:109], v[64:79]
	ds_read_b128 v[208:211], v194 offset:29184
	v_add_f32_e32 v176, v56, v176
	v_add_f32_e32 v177, v57, v177
	v_cvt_pk_bf16_f32 v52, v56, v57
	v_add_f32_e32 v176, v58, v176
	s_waitcnt lgkmcnt(12)
	v_mfma_f32_32x32x16_bf16 v[80:95], v[212:215], v[114:117], v[80:95]
	ds_read_b128 v[212:215], v194 offset:30720
	v_add_f32_e32 v177, v59, v177
	v_cvt_pk_bf16_f32 v53, v58, v59
	v_exp_f32_e32 v60, v60
	v_exp_f32_e32 v61, v61
	s_waitcnt lgkmcnt(9)
	v_mfma_f32_32x32x16_bf16 v[0:15], v[48:51], v[220:223], v[0:15]
	ds_read_b64_tr_b16 v[220:221], v139 offset:2048
	ds_read_b64_tr_b16 v[222:223], v139 offset:2560
	v_exp_f32_e32 v62, v62
	v_exp_f32_e32 v63, v63
	v_add_f32_e32 v176, v60, v176
	v_add_f32_e32 v177, v61, v177
	v_mfma_f32_32x32x16_bf16 v[16:31], v[48:51], v[244:247], v[16:31]
	ds_read_b64_tr_b16 v[244:245], v139 offset:6144
	ds_read_b64_tr_b16 v[246:247], v139 offset:6656
	v_cvt_pk_bf16_f32 v54, v60, v61
	v_add_f32_e32 v176, v62, v176
	v_add_f32_e32 v177, v63, v177
	v_cvt_pk_bf16_f32 v55, v62, v63
	v_mfma_f32_32x32x16_bf16 v[64:79], v[216:219], v[114:117], v[64:79]
	ds_read_b128 v[216:219], v194 offset:31232
	v_exp_f32_e32 v32, v32
	v_exp_f32_e32 v33, v33
	v_exp_f32_e32 v34, v34
	v_exp_f32_e32 v35, v35
	s_waitcnt lgkmcnt(10)
	v_mfma_f32_32x32x16_bf16 v[80:95], v[196:199], v[118:121], v[80:95]
	v_add_f32_e32 v176, v32, v176
	v_add_f32_e32 v177, v33, v177
	v_cvt_pk_bf16_f32 v32, v32, v33
	v_add_f32_e32 v176, v34, v176
	v_mfma_f32_32x32x16_bf16 v[64:79], v[200:203], v[118:121], v[64:79]
	v_add_f32_e32 v177, v35, v177
	v_cvt_pk_bf16_f32 v33, v34, v35
	v_exp_f32_e32 v36, v36
	v_exp_f32_e32 v37, v37
	s_waitcnt lgkmcnt(8)
	v_mfma_f32_32x32x16_bf16 v[0:15], v[52:55], v[240:243], v[0:15]
	ds_read_b64_tr_b16 v[240:241], v139 offset:3072
	ds_read_b64_tr_b16 v[242:243], v139 offset:3584
	v_exp_f32_e32 v38, v38
	v_exp_f32_e32 v39, v39
	v_add_f32_e32 v176, v36, v176
	v_add_f32_e32 v177, v37, v177
	v_mfma_f32_32x32x16_bf16 v[16:31], v[52:55], v[122:125], v[16:31]
	ds_read_b64_tr_b16 v[122:123], v139 offset:7168
	ds_read_b64_tr_b16 v[124:125], v139 offset:7680
	v_cvt_pk_bf16_f32 v34, v36, v37
	v_add_f32_e32 v176, v38, v176
	v_add_f32_e32 v177, v39, v177
	v_cvt_pk_bf16_f32 v35, v38, v39
	s_waitcnt lgkmcnt(10)
	v_mfma_f32_32x32x16_bf16 v[80:95], v[204:207], v[102:105], v[80:95]
	v_exp_f32_e32 v40, v40
	v_exp_f32_e32 v41, v41
	v_exp_f32_e32 v42, v42
	v_exp_f32_e32 v43, v43
	v_mfma_f32_32x32x16_bf16 v[64:79], v[208:211], v[102:105], v[64:79]
	v_add_f32_e32 v176, v40, v176
	v_add_f32_e32 v177, v41, v177
	v_cvt_pk_bf16_f32 v36, v40, v41
	v_add_f32_e32 v176, v42, v176
	s_waitcnt lgkmcnt(5)
	v_mfma_f32_32x32x16_bf16 v[0:15], v[32:35], v[220:223], v[0:15]
	v_add_f32_e32 v177, v43, v177
	v_cvt_pk_bf16_f32 v37, v42, v43
	v_exp_f32_e32 v44, v44
	v_exp_f32_e32 v45, v45
	v_mfma_f32_32x32x16_bf16 v[16:31], v[32:35], v[244:247], v[16:31]
	v_exp_f32_e32 v46, v46
	v_exp_f32_e32 v47, v47
	v_add_f32_e32 v176, v44, v176
	v_add_f32_e32 v177, v45, v177
	s_waitcnt lgkmcnt(4)
	v_mfma_f32_32x32x16_bf16 v[80:95], v[212:215], v[98:101], v[80:95]
	v_cvt_pk_bf16_f32 v38, v44, v45
	v_add_f32_e32 v176, v46, v176
	v_add_f32_e32 v177, v47, v177
	v_cvt_pk_bf16_f32 v39, v46, v47
	v_mfma_f32_32x32x16_bf16 v[64:79], v[216:219], v[98:101], v[64:79]
	v_add_f32_e32 v175, v176, v177
	v_mov_b32_e32 v178, v175
	v_add_f32_e32 v147, v147, v175
	s_nop 0
	s_waitcnt lgkmcnt(0)
	v_mfma_f32_32x32x16_bf16 v[0:15], v[36:39], v[240:243], v[0:15]
	v_permlane32_swap_b32_e32 v175, v178
	v_add_f32_e32 v175, v175, v178
	v_cmp_lt_f32_e32 vcc, 0x43800000, v175
	v_mfma_f32_32x32x16_bf16 v[16:31], v[36:39], v[122:125], v[16:31]
	s_cbranch_vccz .Lat_nr_14
	v_log_f32_e32 v175, v175
	s_nop 0
	v_max_f32_e32 v175, 0, v175
	v_exp_f32_e64 v178, -v175
	s_and_saveexec_b64 s[4:5], s[2:3]
	ds_write_b32 v143, v178 offset:40960
	s_or_b64 exec, exec, s[4:5]
	s_waitcnt lgkmcnt(0)
	v_add_u32_e32 v179, s33, v191
	v_sub_f32_e32 v224, v224, v175
	v_mul_f32_e32 v147, v147, v178
	ds_read_b128 v[196:199], v179 offset:40960
	ds_read_b128 v[200:203], v179 offset:40992
	ds_read_b128 v[204:207], v179 offset:41024
	ds_read_b128 v[208:211], v179 offset:41056
	s_waitcnt lgkmcnt(0)
	s_nop 15
	v_pk_mul_f32 v[0:1], v[0:1], v[196:197]
	v_pk_mul_f32 v[2:3], v[2:3], v[198:199]
	v_pk_mul_f32 v[4:5], v[4:5], v[200:201]
	v_pk_mul_f32 v[6:7], v[6:7], v[202:203]
	v_pk_mul_f32 v[8:9], v[8:9], v[204:205]
	v_pk_mul_f32 v[10:11], v[10:11], v[206:207]
	v_pk_mul_f32 v[12:13], v[12:13], v[208:209]
	v_pk_mul_f32 v[14:15], v[14:15], v[210:211]
	v_pk_mul_f32 v[16:17], v[16:17], v[196:197]
	v_pk_mul_f32 v[18:19], v[18:19], v[198:199]
	v_pk_mul_f32 v[20:21], v[20:21], v[200:201]
	v_pk_mul_f32 v[22:23], v[22:23], v[202:203]
	v_pk_mul_f32 v[24:25], v[24:25], v[204:205]
	v_pk_mul_f32 v[26:27], v[26:27], v[206:207]
	v_pk_mul_f32 v[28:29], v[28:29], v[208:209]
	v_pk_mul_f32 v[30:31], v[30:31], v[210:211]
	v_mov_b32_e32 v225, v224
	v_mov_b32_e32 v226, v224
	v_mov_b32_e32 v227, v224
	v_mov_b32_e32 v228, v224
	v_mov_b32_e32 v229, v224
	v_mov_b32_e32 v230, v224
	v_mov_b32_e32 v231, v224
	v_mov_b32_e32 v232, v224
	v_mov_b32_e32 v233, v224
	v_mov_b32_e32 v234, v224
	v_mov_b32_e32 v235, v224
	v_mov_b32_e32 v236, v224
	v_mov_b32_e32 v237, v224
	v_mov_b32_e32 v238, v224
	v_mov_b32_e32 v239, v224
	v_sub_f32_e32 v80, v80, v175
	v_sub_f32_e32 v81, v81, v175
	v_sub_f32_e32 v82, v82, v175
	v_sub_f32_e32 v83, v83, v175
	v_sub_f32_e32 v84, v84, v175
	v_sub_f32_e32 v85, v85, v175
	v_sub_f32_e32 v86, v86, v175
	v_sub_f32_e32 v87, v87, v175
	v_sub_f32_e32 v88, v88, v175
	v_sub_f32_e32 v89, v89, v175
	v_sub_f32_e32 v90, v90, v175
	v_sub_f32_e32 v91, v91, v175
	v_sub_f32_e32 v92, v92, v175
	v_sub_f32_e32 v93, v93, v175
	v_sub_f32_e32 v94, v94, v175
	v_sub_f32_e32 v95, v95, v175
	v_sub_f32_e32 v64, v64, v175
	v_sub_f32_e32 v65, v65, v175
	v_sub_f32_e32 v66, v66, v175
	v_sub_f32_e32 v67, v67, v175
	v_sub_f32_e32 v68, v68, v175
	v_sub_f32_e32 v69, v69, v175
	v_sub_f32_e32 v70, v70, v175
	v_sub_f32_e32 v71, v71, v175
	v_sub_f32_e32 v72, v72, v175
	v_sub_f32_e32 v73, v73, v175
	v_sub_f32_e32 v74, v74, v175
	v_sub_f32_e32 v75, v75, v175
	v_sub_f32_e32 v76, v76, v175
	v_sub_f32_e32 v77, v77, v175
	v_sub_f32_e32 v78, v78, v175
	v_sub_f32_e32 v79, v79, v175
.Lat_nr_14:
	s_waitcnt vmcnt(2)
	s_barrier
	ds_read_b128 v[196:199], v126 offset:0
	ds_read_b128 v[200:203], v126 offset:512
	ds_read_b128 v[204:207], v126 offset:2048
	ds_read_b128 v[208:211], v126 offset:2560
	ds_read_b128 v[212:215], v126 offset:4096
	ds_read_b128 v[216:219], v126 offset:4608
	ds_read_b64_tr_b16 v[220:221], v139 offset:20480
	ds_read_b64_tr_b16 v[222:223], v139 offset:20992
	ds_read_b64_tr_b16 v[244:245], v139 offset:24576
	ds_read_b64_tr_b16 v[246:247], v139 offset:25088
	s_mov_b64 s[12:13], s[36:37]
	s_add_i32 m0, s22, 0x0
	s_cmp_eq_u32 s23, 0
	global_load_lds_dwordx4 v128, s[12:13]
	s_cbranch_scc1 .Lat_k2_15
	s_add_i32 m0, s22, 0x2000
	s_nop 0
	global_load_lds_dwordx4 v129, s[12:13]
.Lat_k2_15:
	s_add_u32 s12, s12, 0x30000
	s_addc_u32 s13, s13, 0
	s_add_i32 m0, s22, 0x18000
	s_nop 0
	global_load_lds_dwordx4 v145, s[14:15]
	v_exp_f32_e32 v80, v80
	v_exp_f32_e32 v81, v81
	v_exp_f32_e32 v82, v82
	v_exp_f32_e32 v83, v83
	v_mov_b32_e32 v176, v80
	v_mov_b32_e32 v177, v81
	v_cvt_pk_bf16_f32 v80, v80, v81
	v_add_f32_e32 v176, v82, v176
	v_add_f32_e32 v177, v83, v177
	v_cvt_pk_bf16_f32 v81, v82, v83
	v_exp_f32_e32 v84, v84
	v_exp_f32_e32 v85, v85
	s_waitcnt lgkmcnt(8)
	v_mfma_f32_32x32x16_bf16 v[48:63], v[196:199], v[110:113], v[224:239]
	ds_read_b128 v[196:199], v126 offset:6144
	ds_read_b64_tr_b16 v[240:241], v139 offset:21504
	ds_read_b64_tr_b16 v[242:243], v139 offset:22016
	v_exp_f32_e32 v86, v86
	v_exp_f32_e32 v87, v87
	v_add_f32_e32 v176, v84, v176
	v_add_f32_e32 v177, v85, v177
	v_mfma_f32_32x32x16_bf16 v[32:47], v[200:203], v[110:113], v[224:239]
	ds_read_b128 v[200:203], v126 offset:6656
	ds_read_b64_tr_b16 v[122:123], v139 offset:25600
	ds_read_b64_tr_b16 v[124:125], v139 offset:26112
	v_cvt_pk_bf16_f32 v82, v84, v85
	v_add_f32_e32 v176, v86, v176
	v_add_f32_e32 v177, v87, v177
	v_cvt_pk_bf16_f32 v83, v86, v87
	s_waitcnt lgkmcnt(12)
	v_mfma_f32_32x32x16_bf16 v[48:63], v[204:207], v[106:109], v[48:63]
	ds_read_b128 v[204:207], v126 offset:8192
	v_exp_f32_e32 v88, v88
	v_exp_f32_e32 v89, v89
	v_exp_f32_e32 v90, v90
	v_exp_f32_e32 v91, v91
	v_mfma_f32_32x32x16_bf16 v[32:47], v[208:211], v[106:109], v[32:47]
	ds_read_b128 v[208:211], v126 offset:8704
	v_add_f32_e32 v176, v88, v176
	v_add_f32_e32 v177, v89, v177
	v_cvt_pk_bf16_f32 v84, v88, v89
	v_add_f32_e32 v176, v90, v176
	s_waitcnt lgkmcnt(12)
	v_mfma_f32_32x32x16_bf16 v[48:63], v[212:215], v[114:117], v[48:63]
	ds_read_b128 v[212:215], v126 offset:10240
	v_add_f32_e32 v177, v91, v177
	v_cvt_pk_bf16_f32 v85, v90, v91
	v_exp_f32_e32 v92, v92
	v_exp_f32_e32 v93, v93
	s_waitcnt lgkmcnt(9)
	v_mfma_f32_32x32x16_bf16 v[0:15], v[80:83], v[220:223], v[0:15]
	ds_read_b64_tr_b16 v[220:221], v139 offset:22528
	ds_read_b64_tr_b16 v[222:223], v139 offset:23040
	v_exp_f32_e32 v94, v94
	v_exp_f32_e32 v95, v95
	v_add_f32_e32 v176, v92, v176
	v_add_f32_e32 v177, v93, v177
	v_mfma_f32_32x32x16_bf16 v[16:31], v[80:83], v[244:247], v[16:31]
	ds_read_b64_tr_b16 v[244:245], v139 offset:26624
	ds_read_b64_tr_b16 v[246:247], v139 offset:27136
	v_cvt_pk_bf16_f32 v86, v92, v93
	v_add_f32_e32 v176, v94, v176
	v_add_f32_e32 v177, v95, v177
	v_cvt_pk_bf16_f32 v87, v94, v95
	v_mfma_f32_32x32x16_bf16 v[32:47], v[216:219], v[114:117], v[32:47]
	ds_read_b128 v[216:219], v126 offset:10752
	v_exp_f32_e32 v64, v64
	v_exp_f32_e32 v65, v65
	v_exp_f32_e32 v66, v66
	v_exp_f32_e32 v67, v67
	s_waitcnt lgkmcnt(10)
	v_mfma_f32_32x32x16_bf16 v[48:63], v[196:199], v[118:121], v[48:63]
	v_add_f32_e32 v176, v64, v176
	v_add_f32_e32 v177, v65, v177
	v_cvt_pk_bf16_f32 v64, v64, v65
	v_add_f32_e32 v176, v66, v176
	v_mfma_f32_32x32x16_bf16 v[32:47], v[200:203], v[118:121], v[32:47]
	v_add_f32_e32 v177, v67, v177
	v_cvt_pk_bf16_f32 v65, v66, v67
	v_exp_f32_e32 v68, v68
	v_exp_f32_e32 v69, v69
	s_waitcnt lgkmcnt(8)
	v_mfma_f32_32x32x16_bf16 v[0:15], v[84:87], v[240:243], v[0:15]
	ds_read_b64_tr_b16 v[240:241], v139 offset:23552
	ds_read_b64_tr_b16 v[242:243], v139 offset:24064
	v_exp_f32_e32 v70, v70
	v_exp_f32_e32 v71, v71
	v_add_f32_e32 v176, v68, v176
	v_add_f32_e32 v177, v69, v177
	v_mfma_f32_32x32x16_bf16 v[16:31], v[84:87], v[122:125], v[16:31]
	ds_read_b64_tr_b16 v[122:123], v139 offset:27648
	ds_read_b64_tr_b16 v[124:125], v139 offset:28160
	v_cvt_pk_bf16_f32 v66, v68, v69
	v_add_f32_e32 v176, v70, v176
	v_add_f32_e32 v177, v71, v177
	v_cvt_pk_bf16_f32 v67, v70, v71
	s_waitcnt lgkmcnt(10)
	v_mfma_f32_32x32x16_bf16 v[48:63], v[204:207], v[102:105], v[48:63]
	v_exp_f32_e32 v72, v72
	v_exp_f32_e32 v73, v73
	v_exp_f32_e32 v74, v74
	v_exp_f32_e32 v75, v75
	v_mfma_f32_32x32x16_bf16 v[32:47], v[208:211], v[102:105], v[32:47]
	v_add_f32_e32 v176, v72, v176
	v_add_f32_e32 v177, v73, v177
	v_cvt_pk_bf16_f32 v68, v72, v73
	v_add_f32_e32 v176, v74, v176
	s_waitcnt lgkmcnt(5)
	v_mfma_f32_32x32x16_bf16 v[0:15], v[64:67], v[220:223], v[0:15]
	v_add_f32_e32 v177, v75, v177
	v_cvt_pk_bf16_f32 v69, v74, v75
	v_exp_f32_e32 v76, v76
	v_exp_f32_e32 v77, v77
	v_mfma_f32_32x32x16_bf16 v[16:31], v[64:67], v[244:247], v[16:31]
	v_exp_f32_e32 v78, v78
	v_exp_f32_e32 v79, v79
	v_add_f32_e32 v176, v76, v176
	v_add_f32_e32 v177, v77, v177
	s_waitcnt lgkmcnt(4)
	v_mfma_f32_32x32x16_bf16 v[48:63], v[212:215], v[98:101], v[48:63]
	v_cvt_pk_bf16_f32 v70, v76, v77
	v_add_f32_e32 v176, v78, v176
	v_add_f32_e32 v177, v79, v177
	v_cvt_pk_bf16_f32 v71, v78, v79
	v_mfma_f32_32x32x16_bf16 v[32:47], v[216:219], v[98:101], v[32:47]
	v_add_f32_e32 v175, v176, v177
	v_mov_b32_e32 v178, v175
	v_add_f32_e32 v147, v147, v175
	s_nop 0
	s_waitcnt lgkmcnt(0)
	v_mfma_f32_32x32x16_bf16 v[0:15], v[68:71], v[240:243], v[0:15]
	v_permlane32_swap_b32_e32 v175, v178
	v_add_f32_e32 v175, v175, v178
	v_cmp_lt_f32_e32 vcc, 0x43800000, v175
	v_mfma_f32_32x32x16_bf16 v[16:31], v[68:71], v[122:125], v[16:31]
	s_cbranch_vccz .Lat_nr_16
	v_log_f32_e32 v175, v175
	s_nop 0
	v_max_f32_e32 v175, 0, v175
	v_exp_f32_e64 v178, -v175
	s_and_saveexec_b64 s[4:5], s[2:3]
	ds_write_b32 v143, v178 offset:40960
	s_or_b64 exec, exec, s[4:5]
	s_waitcnt lgkmcnt(0)
	v_add_u32_e32 v179, s33, v191
	v_sub_f32_e32 v224, v224, v175
	v_mul_f32_e32 v147, v147, v178
	ds_read_b128 v[196:199], v179 offset:40960
	ds_read_b128 v[200:203], v179 offset:40992
	ds_read_b128 v[204:207], v179 offset:41024
	ds_read_b128 v[208:211], v179 offset:41056
	s_waitcnt lgkmcnt(0)
	s_nop 15
	v_pk_mul_f32 v[0:1], v[0:1], v[196:197]
	v_pk_mul_f32 v[2:3], v[2:3], v[198:199]
	v_pk_mul_f32 v[4:5], v[4:5], v[200:201]
	v_pk_mul_f32 v[6:7], v[6:7], v[202:203]
	v_pk_mul_f32 v[8:9], v[8:9], v[204:205]
	v_pk_mul_f32 v[10:11], v[10:11], v[206:207]
	v_pk_mul_f32 v[12:13], v[12:13], v[208:209]
	v_pk_mul_f32 v[14:15], v[14:15], v[210:211]
	v_pk_mul_f32 v[16:17], v[16:17], v[196:197]
	v_pk_mul_f32 v[18:19], v[18:19], v[198:199]
	v_pk_mul_f32 v[20:21], v[20:21], v[200:201]
	v_pk_mul_f32 v[22:23], v[22:23], v[202:203]
	v_pk_mul_f32 v[24:25], v[24:25], v[204:205]
	v_pk_mul_f32 v[26:27], v[26:27], v[206:207]
	v_pk_mul_f32 v[28:29], v[28:29], v[208:209]
	v_pk_mul_f32 v[30:31], v[30:31], v[210:211]
	v_mov_b32_e32 v225, v224
	v_mov_b32_e32 v226, v224
	v_mov_b32_e32 v227, v224
	v_mov_b32_e32 v228, v224
	v_mov_b32_e32 v229, v224
	v_mov_b32_e32 v230, v224
	v_mov_b32_e32 v231, v224
	v_mov_b32_e32 v232, v224
	v_mov_b32_e32 v233, v224
	v_mov_b32_e32 v234, v224
	v_mov_b32_e32 v235, v224
	v_mov_b32_e32 v236, v224
	v_mov_b32_e32 v237, v224
	v_mov_b32_e32 v238, v224
	v_mov_b32_e32 v239, v224
	v_sub_f32_e32 v48, v48, v175
	v_sub_f32_e32 v49, v49, v175
	v_sub_f32_e32 v50, v50, v175
	v_sub_f32_e32 v51, v51, v175
	v_sub_f32_e32 v52, v52, v175
	v_sub_f32_e32 v53, v53, v175
	v_sub_f32_e32 v54, v54, v175
	v_sub_f32_e32 v55, v55, v175
	v_sub_f32_e32 v56, v56, v175
	v_sub_f32_e32 v57, v57, v175
	v_sub_f32_e32 v58, v58, v175
	v_sub_f32_e32 v59, v59, v175
	v_sub_f32_e32 v60, v60, v175
	v_sub_f32_e32 v61, v61, v175
	v_sub_f32_e32 v62, v62, v175
	v_sub_f32_e32 v63, v63, v175
	v_sub_f32_e32 v32, v32, v175
	v_sub_f32_e32 v33, v33, v175
	v_sub_f32_e32 v34, v34, v175
	v_sub_f32_e32 v35, v35, v175
	v_sub_f32_e32 v36, v36, v175
	v_sub_f32_e32 v37, v37, v175
	v_sub_f32_e32 v38, v38, v175
	v_sub_f32_e32 v39, v39, v175
	v_sub_f32_e32 v40, v40, v175
	v_sub_f32_e32 v41, v41, v175
	v_sub_f32_e32 v42, v42, v175
	v_sub_f32_e32 v43, v43, v175
	v_sub_f32_e32 v44, v44, v175
	v_sub_f32_e32 v45, v45, v175
	v_sub_f32_e32 v46, v46, v175
	v_sub_f32_e32 v47, v47, v175

.Lat_k2_17:
	s_add_u32 s12, s12, 0x30000
	s_addc_u32 s13, s13, 0
	s_mov_b64 s[14:15], s[38:39]
	s_add_i32 m0, s22, 0x3000
	s_nop 0
	global_load_lds_dwordx4 v145, s[14:15]
	s_add_u32 s14, s14, 0x20000
	s_addc_u32 s15, s15, 0
	v_exp_f32_e32 v48, v48
	v_exp_f32_e32 v49, v49
	v_exp_f32_e32 v50, v50
	v_exp_f32_e32 v51, v51
	v_mov_b32_e32 v176, v48
	v_mov_b32_e32 v177, v49
	v_cvt_pk_bf16_f32 v48, v48, v49
	v_add_f32_e32 v176, v50, v176
	v_add_f32_e32 v177, v51, v177
	v_cvt_pk_bf16_f32 v49, v50, v51
	v_exp_f32_e32 v52, v52
	v_exp_f32_e32 v53, v53
	s_waitcnt lgkmcnt(8)
	v_mfma_f32_32x32x16_bf16 v[80:95], v[196:199], v[110:113], v[224:239]
	ds_read_b128 v[196:199], v126 offset:26624
	ds_read_b64_tr_b16 v[240:241], v127 offset:1024
	ds_read_b64_tr_b16 v[242:243], v127 offset:1536
	v_exp_f32_e32 v54, v54
	v_exp_f32_e32 v55, v55
	v_add_f32_e32 v176, v52, v176
	v_add_f32_e32 v177, v53, v177
	v_mfma_f32_32x32x16_bf16 v[64:79], v[200:203], v[110:113], v[224:239]
	ds_read_b128 v[200:203], v126 offset:27136
	ds_read_b64_tr_b16 v[122:123], v127 offset:5120
	ds_read_b64_tr_b16 v[124:125], v127 offset:5632
	v_cvt_pk_bf16_f32 v50, v52, v53
	v_add_f32_e32 v176, v54, v176
	v_add_f32_e32 v177, v55, v177
	v_cvt_pk_bf16_f32 v51, v54, v55
	s_waitcnt lgkmcnt(12)
	v_mfma_f32_32x32x16_bf16 v[80:95], v[204:207], v[106:109], v[80:95]
	ds_read_b128 v[204:207], v126 offset:28672
	v_exp_f32_e32 v56, v56
	v_exp_f32_e32 v57, v57
	v_exp_f32_e32 v58, v58
	v_exp_f32_e32 v59, v59
	v_mfma_f32_32x32x16_bf16 v[64:79], v[208:211], v[106:109], v[64:79]
	ds_read_b128 v[208:211], v126 offset:29184
	v_add_f32_e32 v176, v56, v176
	v_add_f32_e32 v177, v57, v177
	v_cvt_pk_bf16_f32 v52, v56, v57
	v_add_f32_e32 v176, v58, v176
	s_waitcnt lgkmcnt(12)
	v_mfma_f32_32x32x16_bf16 v[80:95], v[212:215], v[114:117], v[80:95]
	ds_read_b128 v[212:215], v126 offset:30720
	v_add_f32_e32 v177, v59, v177
	v_cvt_pk_bf16_f32 v53, v58, v59
	v_exp_f32_e32 v60, v60
	v_exp_f32_e32 v61, v61
	s_waitcnt lgkmcnt(9)
	v_mfma_f32_32x32x16_bf16 v[0:15], v[48:51], v[220:223], v[0:15]
	ds_read_b64_tr_b16 v[220:221], v127 offset:2048
	ds_read_b64_tr_b16 v[222:223], v127 offset:2560
	v_exp_f32_e32 v62, v62
	v_exp_f32_e32 v63, v63
	v_add_f32_e32 v176, v60, v176
	v_add_f32_e32 v177, v61, v177
	v_mfma_f32_32x32x16_bf16 v[16:31], v[48:51], v[244:247], v[16:31]
	ds_read_b64_tr_b16 v[244:245], v127 offset:6144
	ds_read_b64_tr_b16 v[246:247], v127 offset:6656
	v_cvt_pk_bf16_f32 v54, v60, v61
	v_add_f32_e32 v176, v62, v176
	v_add_f32_e32 v177, v63, v177
	v_cvt_pk_bf16_f32 v55, v62, v63
	v_mfma_f32_32x32x16_bf16 v[64:79], v[216:219], v[114:117], v[64:79]
	ds_read_b128 v[216:219], v126 offset:31232
	v_exp_f32_e32 v32, v32
	v_exp_f32_e32 v33, v33
	v_exp_f32_e32 v34, v34
	v_exp_f32_e32 v35, v35
	s_waitcnt lgkmcnt(10)
	v_mfma_f32_32x32x16_bf16 v[80:95], v[196:199], v[118:121], v[80:95]
	v_add_f32_e32 v176, v32, v176
	v_add_f32_e32 v177, v33, v177
	v_cvt_pk_bf16_f32 v32, v32, v33
	v_add_f32_e32 v176, v34, v176
	v_mfma_f32_32x32x16_bf16 v[64:79], v[200:203], v[118:121], v[64:79]
	v_add_f32_e32 v177, v35, v177
	v_cvt_pk_bf16_f32 v33, v34, v35
	v_exp_f32_e32 v36, v36
	v_exp_f32_e32 v37, v37
	s_waitcnt lgkmcnt(8)
	v_mfma_f32_32x32x16_bf16 v[0:15], v[52:55], v[240:243], v[0:15]
	ds_read_b64_tr_b16 v[240:241], v127 offset:3072
	ds_read_b64_tr_b16 v[242:243], v127 offset:3584
	v_exp_f32_e32 v38, v38
	v_exp_f32_e32 v39, v39
	v_add_f32_e32 v176, v36, v176
	v_add_f32_e32 v177, v37, v177
	v_mfma_f32_32x32x16_bf16 v[16:31], v[52:55], v[122:125], v[16:31]
	ds_read_b64_tr_b16 v[122:123], v127 offset:7168
	ds_read_b64_tr_b16 v[124:125], v127 offset:7680
	v_cvt_pk_bf16_f32 v34, v36, v37
	v_add_f32_e32 v176, v38, v176
	v_add_f32_e32 v177, v39, v177
	v_cvt_pk_bf16_f32 v35, v38, v39
	s_waitcnt lgkmcnt(10)
	v_mfma_f32_32x32x16_bf16 v[80:95], v[204:207], v[102:105], v[80:95]
	v_exp_f32_e32 v40, v40
	v_exp_f32_e32 v41, v41
	v_exp_f32_e32 v42, v42
	v_exp_f32_e32 v43, v43
	v_mfma_f32_32x32x16_bf16 v[64:79], v[208:211], v[102:105], v[64:79]
	v_add_f32_e32 v176, v40, v176
	v_add_f32_e32 v177, v41, v177
	v_cvt_pk_bf16_f32 v36, v40, v41
	v_add_f32_e32 v176, v42, v176
	s_waitcnt lgkmcnt(5)
	v_mfma_f32_32x32x16_bf16 v[0:15], v[32:35], v[220:223], v[0:15]
	v_add_f32_e32 v177, v43, v177
	v_cvt_pk_bf16_f32 v37, v42, v43
	v_exp_f32_e32 v44, v44
	v_exp_f32_e32 v45, v45
	v_mfma_f32_32x32x16_bf16 v[16:31], v[32:35], v[244:247], v[16:31]
	v_exp_f32_e32 v46, v46
	v_exp_f32_e32 v47, v47
	v_add_f32_e32 v176, v44, v176
	v_add_f32_e32 v177, v45, v177
	s_waitcnt lgkmcnt(4)
	v_mfma_f32_32x32x16_bf16 v[80:95], v[212:215], v[98:101], v[80:95]
	v_cvt_pk_bf16_f32 v38, v44, v45
	v_add_f32_e32 v176, v46, v176
	v_add_f32_e32 v177, v47, v177
	v_cvt_pk_bf16_f32 v39, v46, v47
	v_mfma_f32_32x32x16_bf16 v[64:79], v[216:219], v[98:101], v[64:79]
	v_add_f32_e32 v175, v176, v177
	v_mov_b32_e32 v178, v175
	v_add_f32_e32 v147, v147, v175
	s_nop 0
	s_waitcnt lgkmcnt(0)
	v_mfma_f32_32x32x16_bf16 v[0:15], v[36:39], v[240:243], v[0:15]
	v_permlane32_swap_b32_e32 v175, v178
	v_add_f32_e32 v175, v175, v178
	v_cmp_lt_f32_e32 vcc, 0x43800000, v175
	v_mfma_f32_32x32x16_bf16 v[16:31], v[36:39], v[122:125], v[16:31]
	s_cbranch_vccz .Lat_nr_18
	v_log_f32_e32 v175, v175
	s_nop 0
	v_max_f32_e32 v175, 0, v175
	v_exp_f32_e64 v178, -v175
	s_and_saveexec_b64 s[4:5], s[2:3]
	ds_write_b32 v143, v178 offset:40960
	s_or_b64 exec, exec, s[4:5]
	s_waitcnt lgkmcnt(0)
	v_add_u32_e32 v179, s33, v191
	v_sub_f32_e32 v224, v224, v175
	v_mul_f32_e32 v147, v147, v178
	ds_read_b128 v[196:199], v179 offset:40960
	ds_read_b128 v[200:203], v179 offset:40992
	ds_read_b128 v[204:207], v179 offset:41024
	ds_read_b128 v[208:211], v179 offset:41056
	s_waitcnt lgkmcnt(0)
	s_nop 15
	v_pk_mul_f32 v[0:1], v[0:1], v[196:197]
	v_pk_mul_f32 v[2:3], v[2:3], v[198:199]
	v_pk_mul_f32 v[4:5], v[4:5], v[200:201]
	v_pk_mul_f32 v[6:7], v[6:7], v[202:203]
	v_pk_mul_f32 v[8:9], v[8:9], v[204:205]
	v_pk_mul_f32 v[10:11], v[10:11], v[206:207]
	v_pk_mul_f32 v[12:13], v[12:13], v[208:209]
	v_pk_mul_f32 v[14:15], v[14:15], v[210:211]
	v_pk_mul_f32 v[16:17], v[16:17], v[196:197]
	v_pk_mul_f32 v[18:19], v[18:19], v[198:199]
	v_pk_mul_f32 v[20:21], v[20:21], v[200:201]
	v_pk_mul_f32 v[22:23], v[22:23], v[202:203]
	v_pk_mul_f32 v[24:25], v[24:25], v[204:205]
	v_pk_mul_f32 v[26:27], v[26:27], v[206:207]
	v_pk_mul_f32 v[28:29], v[28:29], v[208:209]
	v_pk_mul_f32 v[30:31], v[30:31], v[210:211]
	v_mov_b32_e32 v225, v224
	v_mov_b32_e32 v226, v224
	v_mov_b32_e32 v227, v224
	v_mov_b32_e32 v228, v224
	v_mov_b32_e32 v229, v224
	v_mov_b32_e32 v230, v224
	v_mov_b32_e32 v231, v224
	v_mov_b32_e32 v232, v224
	v_mov_b32_e32 v233, v224
	v_mov_b32_e32 v234, v224
	v_mov_b32_e32 v235, v224
	v_mov_b32_e32 v236, v224
	v_mov_b32_e32 v237, v224
	v_mov_b32_e32 v238, v224
	v_mov_b32_e32 v239, v224
	v_sub_f32_e32 v80, v80, v175
	v_sub_f32_e32 v81, v81, v175
	v_sub_f32_e32 v82, v82, v175
	v_sub_f32_e32 v83, v83, v175
	v_sub_f32_e32 v84, v84, v175
	v_sub_f32_e32 v85, v85, v175
	v_sub_f32_e32 v86, v86, v175
	v_sub_f32_e32 v87, v87, v175
	v_sub_f32_e32 v88, v88, v175
	v_sub_f32_e32 v89, v89, v175
	v_sub_f32_e32 v90, v90, v175
	v_sub_f32_e32 v91, v91, v175
	v_sub_f32_e32 v92, v92, v175
	v_sub_f32_e32 v93, v93, v175
	v_sub_f32_e32 v94, v94, v175
	v_sub_f32_e32 v95, v95, v175
	v_sub_f32_e32 v64, v64, v175
	v_sub_f32_e32 v65, v65, v175
	v_sub_f32_e32 v66, v66, v175
	v_sub_f32_e32 v67, v67, v175
	v_sub_f32_e32 v68, v68, v175
	v_sub_f32_e32 v69, v69, v175
	v_sub_f32_e32 v70, v70, v175
	v_sub_f32_e32 v71, v71, v175
	v_sub_f32_e32 v72, v72, v175
	v_sub_f32_e32 v73, v73, v175
	v_sub_f32_e32 v74, v74, v175
	v_sub_f32_e32 v75, v75, v175
	v_sub_f32_e32 v76, v76, v175
	v_sub_f32_e32 v77, v77, v175
	v_sub_f32_e32 v78, v78, v175
	v_sub_f32_e32 v79, v79, v175

.Lat_nr_20:
	s_waitcnt vmcnt(2)
	s_barrier
	ds_read_b128 v[196:199], v194 offset:20480
	ds_read_b128 v[200:203], v194 offset:20992
	ds_read_b128 v[204:207], v194 offset:22528
	ds_read_b128 v[208:211], v194 offset:23040
	ds_read_b128 v[212:215], v194 offset:24576
	ds_read_b128 v[216:219], v194 offset:25088
	ds_read_b64_tr_b16 v[220:221], v139 offset:0
	ds_read_b64_tr_b16 v[222:223], v139 offset:512
	ds_read_b64_tr_b16 v[244:245], v139 offset:4096
	ds_read_b64_tr_b16 v[246:247], v139 offset:4608
	s_add_i32 m0, s22, 0x15000
	s_cmp_eq_u32 s23, 0
	global_load_lds_dwordx4 v128, s[12:13]
	s_cbranch_scc1 .Lat_k2_21
	s_add_i32 m0, s22, 0x17000
	s_nop 0
	global_load_lds_dwordx4 v129, s[12:13]

.Lat_nr_22:
	s_waitcnt vmcnt(2)
	s_barrier
	ds_read_b128 v[196:199], v126 offset:0
	ds_read_b128 v[200:203], v126 offset:512
	ds_read_b128 v[204:207], v126 offset:2048
	ds_read_b128 v[208:211], v126 offset:2560
	ds_read_b128 v[212:215], v126 offset:4096
	ds_read_b128 v[216:219], v126 offset:4608
	ds_read_b64_tr_b16 v[220:221], v139 offset:20480
	ds_read_b64_tr_b16 v[222:223], v139 offset:20992
	ds_read_b64_tr_b16 v[244:245], v139 offset:24576
	ds_read_b64_tr_b16 v[246:247], v139 offset:25088
	s_add_i32 m0, s22, 0x18000
	s_nop 0
	global_load_lds_dwordx4 v145, s[14:15]
	v_exp_f32_e32 v80, v80
	v_exp_f32_e32 v81, v81
	v_exp_f32_e32 v82, v82
	v_exp_f32_e32 v83, v83
	v_mov_b32_e32 v176, v80
	v_mov_b32_e32 v177, v81
	v_cvt_pk_bf16_f32 v80, v80, v81
	v_add_f32_e32 v176, v82, v176
	v_add_f32_e32 v177, v83, v177
	v_cvt_pk_bf16_f32 v81, v82, v83
	v_exp_f32_e32 v84, v84
	v_exp_f32_e32 v85, v85
	s_waitcnt lgkmcnt(8)
	v_mfma_f32_32x32x16_bf16 v[48:63], v[196:199], v[110:113], v[224:239]
	ds_read_b128 v[196:199], v126 offset:6144
	ds_read_b64_tr_b16 v[240:241], v139 offset:21504
	ds_read_b64_tr_b16 v[242:243], v139 offset:22016
	v_exp_f32_e32 v86, v86
	v_exp_f32_e32 v87, v87
	v_add_f32_e32 v176, v84, v176
	v_add_f32_e32 v177, v85, v177
	v_mfma_f32_32x32x16_bf16 v[32:47], v[200:203], v[110:113], v[224:239]
	ds_read_b128 v[200:203], v126 offset:6656
	ds_read_b64_tr_b16 v[122:123], v139 offset:25600
	ds_read_b64_tr_b16 v[124:125], v139 offset:26112
	v_cvt_pk_bf16_f32 v82, v84, v85
	v_add_f32_e32 v176, v86, v176
	v_add_f32_e32 v177, v87, v177
	v_cvt_pk_bf16_f32 v83, v86, v87
	s_waitcnt lgkmcnt(12)
	v_mfma_f32_32x32x16_bf16 v[48:63], v[204:207], v[106:109], v[48:63]
	ds_read_b128 v[204:207], v126 offset:8192
	v_exp_f32_e32 v88, v88
	v_exp_f32_e32 v89, v89
	v_exp_f32_e32 v90, v90
	v_exp_f32_e32 v91, v91
	v_mfma_f32_32x32x16_bf16 v[32:47], v[208:211], v[106:109], v[32:47]
	ds_read_b128 v[208:211], v126 offset:8704
	v_add_f32_e32 v176, v88, v176
	v_add_f32_e32 v177, v89, v177
	v_cvt_pk_bf16_f32 v84, v88, v89
	v_add_f32_e32 v176, v90, v176
	s_waitcnt lgkmcnt(12)
	v_mfma_f32_32x32x16_bf16 v[48:63], v[212:215], v[114:117], v[48:63]
	ds_read_b128 v[212:215], v126 offset:10240
	v_add_f32_e32 v177, v91, v177
	v_cvt_pk_bf16_f32 v85, v90, v91
	v_exp_f32_e32 v92, v92
	v_exp_f32_e32 v93, v93
	s_waitcnt lgkmcnt(9)
	v_mfma_f32_32x32x16_bf16 v[0:15], v[80:83], v[220:223], v[0:15]
	ds_read_b64_tr_b16 v[220:221], v139 offset:22528
	ds_read_b64_tr_b16 v[222:223], v139 offset:23040
	v_exp_f32_e32 v94, v94
	v_exp_f32_e32 v95, v95
	v_add_f32_e32 v176, v92, v176
	v_add_f32_e32 v177, v93, v177
	v_mfma_f32_32x32x16_bf16 v[16:31], v[80:83], v[244:247], v[16:31]
	ds_read_b64_tr_b16 v[244:245], v139 offset:26624
	ds_read_b64_tr_b16 v[246:247], v139 offset:27136
	v_cvt_pk_bf16_f32 v86, v92, v93
	v_add_f32_e32 v176, v94, v176
	v_add_f32_e32 v177, v95, v177
	v_cvt_pk_bf16_f32 v87, v94, v95
	v_mfma_f32_32x32x16_bf16 v[32:47], v[216:219], v[114:117], v[32:47]
	ds_read_b128 v[216:219], v126 offset:10752
	v_exp_f32_e32 v64, v64
	v_exp_f32_e32 v65, v65
	v_exp_f32_e32 v66, v66
	v_exp_f32_e32 v67, v67
	s_waitcnt lgkmcnt(10)
	v_mfma_f32_32x32x16_bf16 v[48:63], v[196:199], v[118:121], v[48:63]
	v_add_f32_e32 v176, v64, v176
	v_add_f32_e32 v177, v65, v177
	v_cvt_pk_bf16_f32 v64, v64, v65
	v_add_f32_e32 v176, v66, v176
	v_mfma_f32_32x32x16_bf16 v[32:47], v[200:203], v[118:121], v[32:47]
	v_add_f32_e32 v177, v67, v177
	v_cvt_pk_bf16_f32 v65, v66, v67
	v_exp_f32_e32 v68, v68
	v_exp_f32_e32 v69, v69
	s_waitcnt lgkmcnt(8)
	v_mfma_f32_32x32x16_bf16 v[0:15], v[84:87], v[240:243], v[0:15]
	ds_read_b64_tr_b16 v[240:241], v139 offset:23552
	ds_read_b64_tr_b16 v[242:243], v139 offset:24064
	v_exp_f32_e32 v70, v70
	v_exp_f32_e32 v71, v71
	v_add_f32_e32 v176, v68, v176
	v_add_f32_e32 v177, v69, v177
	v_mfma_f32_32x32x16_bf16 v[16:31], v[84:87], v[122:125], v[16:31]
	ds_read_b64_tr_b16 v[122:123], v139 offset:27648
	ds_read_b64_tr_b16 v[124:125], v139 offset:28160
	v_cvt_pk_bf16_f32 v66, v68, v69
	v_add_f32_e32 v176, v70, v176
	v_add_f32_e32 v177, v71, v177
	v_cvt_pk_bf16_f32 v67, v70, v71
	s_waitcnt lgkmcnt(10)
	v_mfma_f32_32x32x16_bf16 v[48:63], v[204:207], v[102:105], v[48:63]
	v_exp_f32_e32 v72, v72
	v_exp_f32_e32 v73, v73
	v_exp_f32_e32 v74, v74
	v_exp_f32_e32 v75, v75
	v_mfma_f32_32x32x16_bf16 v[32:47], v[208:211], v[102:105], v[32:47]
	v_add_f32_e32 v176, v72, v176
	v_add_f32_e32 v177, v73, v177
	v_cvt_pk_bf16_f32 v68, v72, v73
	v_add_f32_e32 v176, v74, v176
	s_waitcnt lgkmcnt(5)
	v_mfma_f32_32x32x16_bf16 v[0:15], v[64:67], v[220:223], v[0:15]
	v_add_f32_e32 v177, v75, v177
	v_cvt_pk_bf16_f32 v69, v74, v75
	v_exp_f32_e32 v76, v76
	v_exp_f32_e32 v77, v77
	v_mfma_f32_32x32x16_bf16 v[16:31], v[64:67], v[244:247], v[16:31]
	v_exp_f32_e32 v78, v78
	v_exp_f32_e32 v79, v79
	v_add_f32_e32 v176, v76, v176
	v_add_f32_e32 v177, v77, v177
	s_waitcnt lgkmcnt(4)
	v_mfma_f32_32x32x16_bf16 v[48:63], v[212:215], v[98:101], v[48:63]
	v_cvt_pk_bf16_f32 v70, v76, v77
	v_add_f32_e32 v176, v78, v176
	v_add_f32_e32 v177, v79, v177
	v_cvt_pk_bf16_f32 v71, v78, v79
	v_mfma_f32_32x32x16_bf16 v[32:47], v[216:219], v[98:101], v[32:47]
	v_add_f32_e32 v175, v176, v177
	v_mov_b32_e32 v178, v175
	v_add_f32_e32 v147, v147, v175
	s_nop 0
	s_waitcnt lgkmcnt(0)
	v_mfma_f32_32x32x16_bf16 v[0:15], v[68:71], v[240:243], v[0:15]
	v_permlane32_swap_b32_e32 v175, v178
	v_add_f32_e32 v175, v175, v178
	v_cmp_lt_f32_e32 vcc, 0x43800000, v175
	v_mfma_f32_32x32x16_bf16 v[16:31], v[68:71], v[122:125], v[16:31]
	s_cbranch_vccz .Lat_nr_23
	v_log_f32_e32 v175, v175
	s_nop 0
	v_max_f32_e32 v175, 0, v175
	v_exp_f32_e64 v178, -v175
	s_and_saveexec_b64 s[4:5], s[2:3]
	ds_write_b32 v143, v178 offset:40960
	s_or_b64 exec, exec, s[4:5]
	s_waitcnt lgkmcnt(0)
	v_add_u32_e32 v179, s33, v191
	v_sub_f32_e32 v224, v224, v175
	v_mul_f32_e32 v147, v147, v178
	ds_read_b128 v[196:199], v179 offset:40960
	ds_read_b128 v[200:203], v179 offset:40992
	ds_read_b128 v[204:207], v179 offset:41024
	ds_read_b128 v[208:211], v179 offset:41056
	s_waitcnt lgkmcnt(0)
	s_nop 15
	v_pk_mul_f32 v[0:1], v[0:1], v[196:197]
	v_pk_mul_f32 v[2:3], v[2:3], v[198:199]
	v_pk_mul_f32 v[4:5], v[4:5], v[200:201]
	v_pk_mul_f32 v[6:7], v[6:7], v[202:203]
	v_pk_mul_f32 v[8:9], v[8:9], v[204:205]
	v_pk_mul_f32 v[10:11], v[10:11], v[206:207]
	v_pk_mul_f32 v[12:13], v[12:13], v[208:209]
	v_pk_mul_f32 v[14:15], v[14:15], v[210:211]
	v_pk_mul_f32 v[16:17], v[16:17], v[196:197]
	v_pk_mul_f32 v[18:19], v[18:19], v[198:199]
	v_pk_mul_f32 v[20:21], v[20:21], v[200:201]
	v_pk_mul_f32 v[22:23], v[22:23], v[202:203]
	v_pk_mul_f32 v[24:25], v[24:25], v[204:205]
	v_pk_mul_f32 v[26:27], v[26:27], v[206:207]
	v_pk_mul_f32 v[28:29], v[28:29], v[208:209]
	v_pk_mul_f32 v[30:31], v[30:31], v[210:211]
	v_mov_b32_e32 v225, v224
	v_mov_b32_e32 v226, v224
	v_mov_b32_e32 v227, v224
	v_mov_b32_e32 v228, v224
	v_mov_b32_e32 v229, v224
	v_mov_b32_e32 v230, v224
	v_mov_b32_e32 v231, v224
	v_mov_b32_e32 v232, v224
	v_mov_b32_e32 v233, v224
	v_mov_b32_e32 v234, v224
	v_mov_b32_e32 v235, v224
	v_mov_b32_e32 v236, v224
	v_mov_b32_e32 v237, v224
	v_mov_b32_e32 v238, v224
	v_mov_b32_e32 v239, v224
	v_sub_f32_e32 v48, v48, v175
	v_sub_f32_e32 v49, v49, v175
	v_sub_f32_e32 v50, v50, v175
	v_sub_f32_e32 v51, v51, v175
	v_sub_f32_e32 v52, v52, v175
	v_sub_f32_e32 v53, v53, v175
	v_sub_f32_e32 v54, v54, v175
	v_sub_f32_e32 v55, v55, v175
	v_sub_f32_e32 v56, v56, v175
	v_sub_f32_e32 v57, v57, v175
	v_sub_f32_e32 v58, v58, v175
	v_sub_f32_e32 v59, v59, v175
	v_sub_f32_e32 v60, v60, v175
	v_sub_f32_e32 v61, v61, v175
	v_sub_f32_e32 v62, v62, v175
	v_sub_f32_e32 v63, v63, v175
	v_sub_f32_e32 v32, v32, v175
	v_sub_f32_e32 v33, v33, v175
	v_sub_f32_e32 v34, v34, v175
	v_sub_f32_e32 v35, v35, v175
	v_sub_f32_e32 v36, v36, v175
	v_sub_f32_e32 v37, v37, v175
	v_sub_f32_e32 v38, v38, v175
	v_sub_f32_e32 v39, v39, v175
	v_sub_f32_e32 v40, v40, v175
	v_sub_f32_e32 v41, v41, v175
	v_sub_f32_e32 v42, v42, v175
	v_sub_f32_e32 v43, v43, v175
	v_sub_f32_e32 v44, v44, v175
	v_sub_f32_e32 v45, v45, v175
	v_sub_f32_e32 v46, v46, v175
	v_sub_f32_e32 v47, v47, v175
.Lat_nr_23:
	s_waitcnt vmcnt(1)
	s_barrier
	ds_read_b128 v[196:199], v126 offset:20480
	ds_read_b128 v[200:203], v126 offset:20992
	ds_read_b128 v[204:207], v126 offset:22528
	ds_read_b128 v[208:211], v126 offset:23040
	ds_read_b128 v[212:215], v126 offset:24576
	ds_read_b128 v[216:219], v126 offset:25088
	ds_read_b64_tr_b16 v[220:221], v127 offset:0
	ds_read_b64_tr_b16 v[222:223], v127 offset:512
	ds_read_b64_tr_b16 v[244:245], v127 offset:4096
	ds_read_b64_tr_b16 v[246:247], v127 offset:4608
	v_exp_f32_e32 v48, v48
	v_exp_f32_e32 v49, v49
	v_exp_f32_e32 v50, v50
	v_exp_f32_e32 v51, v51
	v_mov_b32_e32 v176, v48
	v_mov_b32_e32 v177, v49
	v_cvt_pk_bf16_f32 v48, v48, v49
	v_add_f32_e32 v176, v50, v176
	v_add_f32_e32 v177, v51, v177
	v_cvt_pk_bf16_f32 v49, v50, v51
	v_exp_f32_e32 v52, v52
	v_exp_f32_e32 v53, v53
	s_waitcnt lgkmcnt(8)
	v_mfma_f32_32x32x16_bf16 v[80:95], v[196:199], v[110:113], v[224:239]
	ds_read_b128 v[196:199], v126 offset:26624
	ds_read_b64_tr_b16 v[240:241], v127 offset:1024
	ds_read_b64_tr_b16 v[242:243], v127 offset:1536
	v_exp_f32_e32 v54, v54
	v_exp_f32_e32 v55, v55
	v_add_f32_e32 v176, v52, v176
	v_add_f32_e32 v177, v53, v177
	v_mfma_f32_32x32x16_bf16 v[64:79], v[200:203], v[110:113], v[224:239]
	ds_read_b128 v[200:203], v126 offset:27136
	ds_read_b64_tr_b16 v[122:123], v127 offset:5120
	ds_read_b64_tr_b16 v[124:125], v127 offset:5632
	v_cvt_pk_bf16_f32 v50, v52, v53
	v_add_f32_e32 v176, v54, v176
	v_add_f32_e32 v177, v55, v177
	v_cvt_pk_bf16_f32 v51, v54, v55
	s_waitcnt lgkmcnt(12)
	v_mfma_f32_32x32x16_bf16 v[80:95], v[204:207], v[106:109], v[80:95]
	ds_read_b128 v[204:207], v126 offset:28672
	v_exp_f32_e32 v56, v56
	v_exp_f32_e32 v57, v57
	v_exp_f32_e32 v58, v58
	v_exp_f32_e32 v59, v59
	v_mfma_f32_32x32x16_bf16 v[64:79], v[208:211], v[106:109], v[64:79]
	ds_read_b128 v[208:211], v126 offset:29184
	v_add_f32_e32 v176, v56, v176
	v_add_f32_e32 v177, v57, v177
	v_cvt_pk_bf16_f32 v52, v56, v57
	v_add_f32_e32 v176, v58, v176
	s_waitcnt lgkmcnt(12)
	v_mfma_f32_32x32x16_bf16 v[80:95], v[212:215], v[114:117], v[80:95]
	ds_read_b128 v[212:215], v126 offset:30720
	v_add_f32_e32 v177, v59, v177
	v_cvt_pk_bf16_f32 v53, v58, v59
	v_exp_f32_e32 v60, v60
	v_exp_f32_e32 v61, v61
	s_waitcnt lgkmcnt(9)
	v_mfma_f32_32x32x16_bf16 v[0:15], v[48:51], v[220:223], v[0:15]
	ds_read_b64_tr_b16 v[220:221], v127 offset:2048
	ds_read_b64_tr_b16 v[222:223], v127 offset:2560
	v_exp_f32_e32 v62, v62
	v_exp_f32_e32 v63, v63
	v_add_f32_e32 v176, v60, v176
	v_add_f32_e32 v177, v61, v177
	v_mfma_f32_32x32x16_bf16 v[16:31], v[48:51], v[244:247], v[16:31]
	ds_read_b64_tr_b16 v[244:245], v127 offset:6144
	ds_read_b64_tr_b16 v[246:247], v127 offset:6656
	v_cvt_pk_bf16_f32 v54, v60, v61
	v_add_f32_e32 v176, v62, v176
	v_add_f32_e32 v177, v63, v177
	v_cvt_pk_bf16_f32 v55, v62, v63
	v_mfma_f32_32x32x16_bf16 v[64:79], v[216:219], v[114:117], v[64:79]
	ds_read_b128 v[216:219], v126 offset:31232
	v_exp_f32_e32 v32, v32
	v_exp_f32_e32 v33, v33
	v_exp_f32_e32 v34, v34
	v_exp_f32_e32 v35, v35
	s_waitcnt lgkmcnt(10)
	v_mfma_f32_32x32x16_bf16 v[80:95], v[196:199], v[118:121], v[80:95]
	v_add_f32_e32 v176, v32, v176
	v_add_f32_e32 v177, v33, v177
	v_cvt_pk_bf16_f32 v32, v32, v33
	v_add_f32_e32 v176, v34, v176
	v_mfma_f32_32x32x16_bf16 v[64:79], v[200:203], v[118:121], v[64:79]
	v_add_f32_e32 v177, v35, v177
	v_cvt_pk_bf16_f32 v33, v34, v35
	v_exp_f32_e32 v36, v36
	v_exp_f32_e32 v37, v37
	s_waitcnt lgkmcnt(8)
	v_mfma_f32_32x32x16_bf16 v[0:15], v[52:55], v[240:243], v[0:15]
	ds_read_b64_tr_b16 v[240:241], v127 offset:3072
	ds_read_b64_tr_b16 v[242:243], v127 offset:3584
	v_exp_f32_e32 v38, v38
	v_exp_f32_e32 v39, v39
	v_add_f32_e32 v176, v36, v176
	v_add_f32_e32 v177, v37, v177
	v_mfma_f32_32x32x16_bf16 v[16:31], v[52:55], v[122:125], v[16:31]
	ds_read_b64_tr_b16 v[122:123], v127 offset:7168
	ds_read_b64_tr_b16 v[124:125], v127 offset:7680
	v_cvt_pk_bf16_f32 v34, v36, v37
	v_add_f32_e32 v176, v38, v176
	v_add_f32_e32 v177, v39, v177
	v_cvt_pk_bf16_f32 v35, v38, v39
	s_waitcnt lgkmcnt(10)
	v_mfma_f32_32x32x16_bf16 v[80:95], v[204:207], v[102:105], v[80:95]
	v_exp_f32_e32 v40, v40
	v_exp_f32_e32 v41, v41
	v_exp_f32_e32 v42, v42
	v_exp_f32_e32 v43, v43
	v_mfma_f32_32x32x16_bf16 v[64:79], v[208:211], v[102:105], v[64:79]
	v_add_f32_e32 v176, v40, v176
	v_add_f32_e32 v177, v41, v177
	v_cvt_pk_bf16_f32 v36, v40, v41
	v_add_f32_e32 v176, v42, v176
	s_waitcnt lgkmcnt(5)
	v_mfma_f32_32x32x16_bf16 v[0:15], v[32:35], v[220:223], v[0:15]
	v_add_f32_e32 v177, v43, v177
	v_cvt_pk_bf16_f32 v37, v42, v43
	v_exp_f32_e32 v44, v44
	v_exp_f32_e32 v45, v45
	v_mfma_f32_32x32x16_bf16 v[16:31], v[32:35], v[244:247], v[16:31]
	v_exp_f32_e32 v46, v46
	v_exp_f32_e32 v47, v47
	v_add_f32_e32 v176, v44, v176
	v_add_f32_e32 v177, v45, v177
	s_waitcnt lgkmcnt(4)
	v_mfma_f32_32x32x16_bf16 v[80:95], v[212:215], v[98:101], v[80:95]
	v_cvt_pk_bf16_f32 v38, v44, v45
	v_add_f32_e32 v176, v46, v176
	v_add_f32_e32 v177, v47, v177
	v_cvt_pk_bf16_f32 v39, v46, v47
	v_mfma_f32_32x32x16_bf16 v[64:79], v[216:219], v[98:101], v[64:79]
	v_add_f32_e32 v175, v176, v177
	v_mov_b32_e32 v178, v175
	v_add_f32_e32 v147, v147, v175
	s_nop 0
	s_waitcnt lgkmcnt(0)
	v_mfma_f32_32x32x16_bf16 v[0:15], v[36:39], v[240:243], v[0:15]
	v_permlane32_swap_b32_e32 v175, v178
	v_add_f32_e32 v175, v175, v178
	v_cmp_lt_f32_e32 vcc, 0x43800000, v175
	v_mfma_f32_32x32x16_bf16 v[16:31], v[36:39], v[122:125], v[16:31]
	s_cbranch_vccz .Lat_nr_24
	v_log_f32_e32 v175, v175
	s_nop 0
	v_max_f32_e32 v175, 0, v175
	v_exp_f32_e64 v178, -v175
	s_and_saveexec_b64 s[4:5], s[2:3]
	ds_write_b32 v143, v178 offset:40960
	s_or_b64 exec, exec, s[4:5]
	s_waitcnt lgkmcnt(0)
	v_add_u32_e32 v179, s33, v191
	v_sub_f32_e32 v224, v224, v175
	v_mul_f32_e32 v147, v147, v178
	ds_read_b128 v[196:199], v179 offset:40960
	ds_read_b128 v[200:203], v179 offset:40992
	ds_read_b128 v[204:207], v179 offset:41024
	ds_read_b128 v[208:211], v179 offset:41056
	s_waitcnt lgkmcnt(0)
	s_nop 15
	v_pk_mul_f32 v[0:1], v[0:1], v[196:197]
	v_pk_mul_f32 v[2:3], v[2:3], v[198:199]
	v_pk_mul_f32 v[4:5], v[4:5], v[200:201]
	v_pk_mul_f32 v[6:7], v[6:7], v[202:203]
	v_pk_mul_f32 v[8:9], v[8:9], v[204:205]
	v_pk_mul_f32 v[10:11], v[10:11], v[206:207]
	v_pk_mul_f32 v[12:13], v[12:13], v[208:209]
	v_pk_mul_f32 v[14:15], v[14:15], v[210:211]
	v_pk_mul_f32 v[16:17], v[16:17], v[196:197]
	v_pk_mul_f32 v[18:19], v[18:19], v[198:199]
	v_pk_mul_f32 v[20:21], v[20:21], v[200:201]
	v_pk_mul_f32 v[22:23], v[22:23], v[202:203]
	v_pk_mul_f32 v[24:25], v[24:25], v[204:205]
	v_pk_mul_f32 v[26:27], v[26:27], v[206:207]
	v_pk_mul_f32 v[28:29], v[28:29], v[208:209]
	v_pk_mul_f32 v[30:31], v[30:31], v[210:211]
	v_mov_b32_e32 v225, v224
	v_mov_b32_e32 v226, v224
	v_mov_b32_e32 v227, v224
	v_mov_b32_e32 v228, v224
	v_mov_b32_e32 v229, v224
	v_mov_b32_e32 v230, v224
	v_mov_b32_e32 v231, v224
	v_mov_b32_e32 v232, v224
	v_mov_b32_e32 v233, v224
	v_mov_b32_e32 v234, v224
	v_mov_b32_e32 v235, v224
	v_mov_b32_e32 v236, v224
	v_mov_b32_e32 v237, v224
	v_mov_b32_e32 v238, v224
	v_mov_b32_e32 v239, v224
	v_sub_f32_e32 v80, v80, v175
	v_sub_f32_e32 v81, v81, v175
	v_sub_f32_e32 v82, v82, v175
	v_sub_f32_e32 v83, v83, v175
	v_sub_f32_e32 v84, v84, v175
	v_sub_f32_e32 v85, v85, v175
	v_sub_f32_e32 v86, v86, v175
	v_sub_f32_e32 v87, v87, v175
	v_sub_f32_e32 v88, v88, v175
	v_sub_f32_e32 v89, v89, v175
	v_sub_f32_e32 v90, v90, v175
	v_sub_f32_e32 v91, v91, v175
	v_sub_f32_e32 v92, v92, v175
	v_sub_f32_e32 v93, v93, v175
	v_sub_f32_e32 v94, v94, v175
	v_sub_f32_e32 v95, v95, v175
	v_sub_f32_e32 v64, v64, v175
	v_sub_f32_e32 v65, v65, v175
	v_sub_f32_e32 v66, v66, v175
	v_sub_f32_e32 v67, v67, v175
	v_sub_f32_e32 v68, v68, v175
	v_sub_f32_e32 v69, v69, v175
	v_sub_f32_e32 v70, v70, v175
	v_sub_f32_e32 v71, v71, v175
	v_sub_f32_e32 v72, v72, v175
	v_sub_f32_e32 v73, v73, v175
	v_sub_f32_e32 v74, v74, v175
	v_sub_f32_e32 v75, v75, v175
	v_sub_f32_e32 v76, v76, v175
	v_sub_f32_e32 v77, v77, v175
	v_sub_f32_e32 v78, v78, v175
	v_sub_f32_e32 v79, v79, v175
.Lat_nr_24:
	s_waitcnt vmcnt(0)
	s_barrier
	ds_read_b64_tr_b16 v[220:221], v127 offset:20480
	ds_read_b64_tr_b16 v[222:223], v127 offset:20992
	ds_read_b64_tr_b16 v[244:245], v127 offset:24576
	ds_read_b64_tr_b16 v[246:247], v127 offset:25088
	v_exp_f32_e32 v80, v80
	v_exp_f32_e32 v81, v81
	v_exp_f32_e32 v82, v82
	v_exp_f32_e32 v83, v83
	v_mov_b32_e32 v176, v80
	v_mov_b32_e32 v177, v81
	v_cvt_pk_bf16_f32 v80, v80, v81
	v_add_f32_e32 v176, v82, v176
	v_add_f32_e32 v177, v83, v177
	v_cvt_pk_bf16_f32 v81, v82, v83
	v_exp_f32_e32 v84, v84
	v_exp_f32_e32 v85, v85
	ds_read_b64_tr_b16 v[240:241], v127 offset:21504
	ds_read_b64_tr_b16 v[242:243], v127 offset:22016
	v_exp_f32_e32 v86, v86
	v_exp_f32_e32 v87, v87
	v_add_f32_e32 v176, v84, v176
	v_add_f32_e32 v177, v85, v177
	ds_read_b64_tr_b16 v[122:123], v127 offset:25600
	ds_read_b64_tr_b16 v[124:125], v127 offset:26112
	v_cvt_pk_bf16_f32 v82, v84, v85
	v_add_f32_e32 v176, v86, v176
	v_add_f32_e32 v177, v87, v177
	v_cvt_pk_bf16_f32 v83, v86, v87
	v_exp_f32_e32 v88, v88
	v_exp_f32_e32 v89, v89
	v_exp_f32_e32 v90, v90
	v_exp_f32_e32 v91, v91
	v_add_f32_e32 v176, v88, v176
	v_add_f32_e32 v177, v89, v177
	v_cvt_pk_bf16_f32 v84, v88, v89
	v_add_f32_e32 v176, v90, v176
	v_add_f32_e32 v177, v91, v177
	v_cvt_pk_bf16_f32 v85, v90, v91
	v_exp_f32_e32 v92, v92
	v_exp_f32_e32 v93, v93
	s_waitcnt lgkmcnt(4)
	v_mfma_f32_32x32x16_bf16 v[0:15], v[80:83], v[220:223], v[0:15]
	ds_read_b64_tr_b16 v[220:221], v127 offset:22528
	ds_read_b64_tr_b16 v[222:223], v127 offset:23040
	v_exp_f32_e32 v94, v94
	v_exp_f32_e32 v95, v95
	v_add_f32_e32 v176, v92, v176
	v_add_f32_e32 v177, v93, v177
	v_mfma_f32_32x32x16_bf16 v[16:31], v[80:83], v[244:247], v[16:31]
	ds_read_b64_tr_b16 v[244:245], v127 offset:26624
	ds_read_b64_tr_b16 v[246:247], v127 offset:27136
	v_cvt_pk_bf16_f32 v86, v92, v93
	v_add_f32_e32 v176, v94, v176
	v_add_f32_e32 v177, v95, v177
	v_cvt_pk_bf16_f32 v87, v94, v95
	v_exp_f32_e32 v64, v64
	v_exp_f32_e32 v65, v65
	v_exp_f32_e32 v66, v66
	v_exp_f32_e32 v67, v67
	v_add_f32_e32 v176, v64, v176
	v_add_f32_e32 v177, v65, v177
	v_cvt_pk_bf16_f32 v64, v64, v65
	v_add_f32_e32 v176, v66, v176
	v_add_f32_e32 v177, v67, v177
	v_cvt_pk_bf16_f32 v65, v66, v67
	v_exp_f32_e32 v68, v68
	v_exp_f32_e32 v69, v69
	s_waitcnt lgkmcnt(4)
	v_mfma_f32_32x32x16_bf16 v[0:15], v[84:87], v[240:243], v[0:15]
	ds_read_b64_tr_b16 v[240:241], v127 offset:23552
	ds_read_b64_tr_b16 v[242:243], v127 offset:24064
	v_exp_f32_e32 v70, v70
	v_exp_f32_e32 v71, v71
	v_add_f32_e32 v176, v68, v176
	v_add_f32_e32 v177, v69, v177
	v_mfma_f32_32x32x16_bf16 v[16:31], v[84:87], v[122:125], v[16:31]
	ds_read_b64_tr_b16 v[122:123], v127 offset:27648
	ds_read_b64_tr_b16 v[124:125], v127 offset:28160
	v_cvt_pk_bf16_f32 v66, v68, v69
	v_add_f32_e32 v176, v70, v176
	v_add_f32_e32 v177, v71, v177
	v_cvt_pk_bf16_f32 v67, v70, v71
	v_exp_f32_e32 v72, v72
	v_exp_f32_e32 v73, v73
	v_exp_f32_e32 v74, v74
	v_exp_f32_e32 v75, v75
	v_add_f32_e32 v176, v72, v176
	v_add_f32_e32 v177, v73, v177
	v_cvt_pk_bf16_f32 v68, v72, v73
	v_add_f32_e32 v176, v74, v176
	s_waitcnt lgkmcnt(4)
	v_mfma_f32_32x32x16_bf16 v[0:15], v[64:67], v[220:223], v[0:15]
	v_add_f32_e32 v177, v75, v177
	v_cvt_pk_bf16_f32 v69, v74, v75
	v_exp_f32_e32 v76, v76
	v_exp_f32_e32 v77, v77
	v_mfma_f32_32x32x16_bf16 v[16:31], v[64:67], v[244:247], v[16:31]
	v_exp_f32_e32 v78, v78
	v_exp_f32_e32 v79, v79
	v_add_f32_e32 v176, v76, v176
	v_add_f32_e32 v177, v77, v177
	v_cvt_pk_bf16_f32 v70, v76, v77
	v_add_f32_e32 v176, v78, v176
	v_add_f32_e32 v177, v79, v177
	v_cvt_pk_bf16_f32 v71, v78, v79
	v_add_f32_e32 v175, v176, v177
	v_mov_b32_e32 v178, v175
	v_add_f32_e32 v147, v147, v175
	s_nop 0
	s_waitcnt lgkmcnt(0)
	v_mfma_f32_32x32x16_bf16 v[0:15], v[68:71], v[240:243], v[0:15]
	v_permlane32_swap_b32_e32 v175, v178
	v_add_f32_e32 v175, v175, v178
	v_cmp_lt_f32_e32 vcc, 0x43800000, v175
	v_mfma_f32_32x32x16_bf16 v[16:31], v[68:71], v[122:125], v[16:31]
	s_cbranch_vccz .Lat_nr_25
	v_log_f32_e32 v175, v175
	s_nop 0
	v_max_f32_e32 v175, 0, v175
	v_exp_f32_e64 v178, -v175
	s_and_saveexec_b64 s[4:5], s[2:3]
	ds_write_b32 v143, v178 offset:40960
	s_or_b64 exec, exec, s[4:5]
	s_waitcnt lgkmcnt(0)
	v_add_u32_e32 v179, s33, v191
	v_sub_f32_e32 v224, v224, v175
	v_mul_f32_e32 v147, v147, v178
	ds_read_b128 v[196:199], v179 offset:40960
	ds_read_b128 v[200:203], v179 offset:40992
	ds_read_b128 v[204:207], v179 offset:41024
	ds_read_b128 v[208:211], v179 offset:41056
	s_waitcnt lgkmcnt(0)
	s_nop 15
	v_pk_mul_f32 v[0:1], v[0:1], v[196:197]
	v_pk_mul_f32 v[2:3], v[2:3], v[198:199]
	v_pk_mul_f32 v[4:5], v[4:5], v[200:201]
	v_pk_mul_f32 v[6:7], v[6:7], v[202:203]
	v_pk_mul_f32 v[8:9], v[8:9], v[204:205]
	v_pk_mul_f32 v[10:11], v[10:11], v[206:207]
	v_pk_mul_f32 v[12:13], v[12:13], v[208:209]
	v_pk_mul_f32 v[14:15], v[14:15], v[210:211]
	v_pk_mul_f32 v[16:17], v[16:17], v[196:197]
	v_pk_mul_f32 v[18:19], v[18:19], v[198:199]
	v_pk_mul_f32 v[20:21], v[20:21], v[200:201]
	v_pk_mul_f32 v[22:23], v[22:23], v[202:203]
	v_pk_mul_f32 v[24:25], v[24:25], v[204:205]
	v_pk_mul_f32 v[26:27], v[26:27], v[206:207]
	v_pk_mul_f32 v[28:29], v[28:29], v[208:209]
	v_pk_mul_f32 v[30:31], v[30:31], v[210:211]
	v_mov_b32_e32 v225, v224
	v_mov_b32_e32 v226, v224
	v_mov_b32_e32 v227, v224
	v_mov_b32_e32 v228, v224
	v_mov_b32_e32 v229, v224
	v_mov_b32_e32 v230, v224
	v_mov_b32_e32 v231, v224
	v_mov_b32_e32 v232, v224
	v_mov_b32_e32 v233, v224
	v_mov_b32_e32 v234, v224
	v_mov_b32_e32 v235, v224
	v_mov_b32_e32 v236, v224
	v_mov_b32_e32 v237, v224
	v_mov_b32_e32 v238, v224
	v_mov_b32_e32 v239, v224
